# GEMM K-loops: LDS-DMA loads issued in SGPR-base + 32-bit VGPR-offset form (stride added by two SALU ops), removing most per-iteration 64-bit vector address adds
# speedup vs baseline: 1.0250x; 1.0026x over previous
.LBB0_159:
	s_ashr_i32 s29, s28, 31
	s_lshl_b64 s[24:25], s[28:29], 19
	s_add_u32 s24, s34, s24
	s_addc_u32 s25, s35, s25
	s_and_b64 s[30:31], s[18:19], exec
	s_cselect_b32 s29, s25, s41
	s_cselect_b32 s43, s24, s40
	s_ashr_i32 s21, s20, 31
	s_lshl_b64 s[30:31], s[20:21], 19
	s_add_u32 s30, s36, s30
	s_addc_u32 s31, s37, s31
	s_and_b64 s[56:57], s[18:19], exec
	s_cselect_b32 s21, s31, s27
	s_cselect_b32 s55, s30, s26
	s_add_u32 s40, s40, 0x40080
	s_addc_u32 s41, s41, 0
	s_add_u32 s56, s26, 0x100
	s_addc_u32 s57, s27, 0
	s_mov_b32 s58, -2
	s_add_u32 s26, s40, 0xfffc0080
	s_addc_u32 s27, s41, -1
	s_add_i32 s59, 0, 0x10000
	s_cmp_eq_u32 s58, 12
	s_cselect_b32 vcc_hi, s29, s27
	s_cselect_b32 vcc_lo, s43, s26
	v_add_u32_e32 v0, s59, v167
	s_cselect_b32 s27, s21, s57
	s_cselect_b32 s26, s55, s56
	s_add_i32 s62, 0, 0x14000
	ds_read_b128 v[142:145], v0
	ds_read_b128 v[146:149], v0 offset:1024
	ds_read_b128 v[150:153], v0 offset:2048
	ds_read_b128 v[154:157], v0 offset:3072
	v_add_u32_e32 v0, s62, v167
	ds_read_b128 v[158:161], v0
	ds_read_b128 v[162:165], v0 offset:1024
	ds_read_b128 v[174:177], v0 offset:2048
	ds_read_b128 v[178:181], v0 offset:3072
	s_add_i32 m0, s23, 0xc000
	ds_read_b128 v[182:185], v173
	ds_read_b128 v[186:189], v173 offset:1024
	ds_read_b128 v[190:193], v173 offset:2048
	ds_read_b128 v[194:197], v173 offset:3072
	ds_read_b128 v[198:201], v173 offset:4096
	ds_read_b128 v[202:205], v173 offset:5120
	ds_read_b128 v[206:209], v173 offset:6144
	ds_read_b128 v[210:213], v173 offset:7168
	global_load_lds_dwordx4 v138, s[40:41]
	s_add_i32 m0, s23, 0xe000
	s_nop 0
	global_load_lds_dwordx4 v140, s[40:41]
	s_waitcnt vmcnt(8)
	s_waitcnt lgkmcnt(0)
	s_barrier
	s_waitcnt lgkmcnt(0)
	v_mfma_f32_16x16x32_bf16 v[126:129], v[142:145], v[182:185], 0
	v_mfma_f32_16x16x32_bf16 v[126:129], v[146:149], v[186:189], v[126:129]
	v_mfma_f32_16x16x32_bf16 v[122:125], v[154:157], v[186:189], 0
	v_mfma_f32_16x16x32_bf16 v[122:125], v[150:153], v[182:185], v[122:125]
	v_mfma_f32_16x16x32_bf16 v[114:117], v[150:153], v[190:193], 0
	v_mfma_f32_16x16x32_bf16 v[114:117], v[154:157], v[194:197], v[114:117]
	v_mfma_f32_16x16x32_bf16 v[118:121], v[146:149], v[194:197], 0
	v_mfma_f32_16x16x32_bf16 v[118:121], v[142:145], v[190:193], v[118:121]
	v_mfma_f32_16x16x32_bf16 v[110:113], v[142:145], v[198:201], 0
	v_mfma_f32_16x16x32_bf16 v[110:113], v[146:149], v[202:205], v[110:113]
	v_mfma_f32_16x16x32_bf16 v[106:109], v[154:157], v[202:205], 0
	v_mfma_f32_16x16x32_bf16 v[106:109], v[150:153], v[198:201], v[106:109]
	v_mfma_f32_16x16x32_bf16 v[98:101], v[150:153], v[206:209], 0
	v_mfma_f32_16x16x32_bf16 v[98:101], v[154:157], v[210:213], v[98:101]
	v_mfma_f32_16x16x32_bf16 v[102:105], v[146:149], v[210:213], 0
	v_mfma_f32_16x16x32_bf16 v[102:105], v[142:145], v[206:209], v[102:105]
	v_mfma_f32_16x16x32_bf16 v[38:41], v[158:161], v[206:209], 0
	v_mfma_f32_16x16x32_bf16 v[38:41], v[162:165], v[210:213], v[38:41]
	v_mfma_f32_16x16x32_bf16 v[34:37], v[178:181], v[210:213], 0
	v_mfma_f32_16x16x32_bf16 v[34:37], v[174:177], v[206:209], v[34:37]
	v_mfma_f32_16x16x32_bf16 v[46:49], v[174:177], v[198:201], 0
	v_mfma_f32_16x16x32_bf16 v[46:49], v[178:181], v[202:205], v[46:49]
	v_mfma_f32_16x16x32_bf16 v[54:57], v[162:165], v[202:205], 0
	v_mfma_f32_16x16x32_bf16 v[54:57], v[158:161], v[198:201], v[54:57]
	v_mfma_f32_16x16x32_bf16 v[70:73], v[158:161], v[190:193], 0
	v_mfma_f32_16x16x32_bf16 v[70:73], v[162:165], v[194:197], v[70:73]
	v_mfma_f32_16x16x32_bf16 v[62:65], v[178:181], v[194:197], 0
	v_mfma_f32_16x16x32_bf16 v[62:65], v[174:177], v[190:193], v[62:65]
	v_mfma_f32_16x16x32_bf16 v[74:77], v[174:177], v[182:185], 0
	v_mfma_f32_16x16x32_bf16 v[74:77], v[178:181], v[186:189], v[74:77]
	v_mfma_f32_16x16x32_bf16 v[82:85], v[162:165], v[186:189], 0
	v_mfma_f32_16x16x32_bf16 v[82:85], v[158:161], v[182:185], v[82:85]
	s_barrier
	s_add_i32 s59, s59, s44
	s_add_u32 s64, s26, s98
	s_addc_u32 s65, s27, s99
	s_mov_b32 m0, s59
	ds_read_b128 v[182:185], v173 offset:16384
	ds_read_b128 v[186:189], v173 offset:17408
	ds_read_b128 v[190:193], v173 offset:18432
	ds_read_b128 v[194:197], v173 offset:19456
	ds_read_b128 v[198:201], v173 offset:20480
	ds_read_b128 v[202:205], v173 offset:21504
	ds_read_b128 v[206:209], v173 offset:22528
	ds_read_b128 v[210:213], v173 offset:23552
	global_load_lds_dwordx4 v132, s[26:27]
	s_add_i32 m0, s59, 0x2000
	s_add_u32 s60, s26, 0x40000
	s_addc_u32 s61, s27, 0
	s_add_i32 s59, s62, s44
	global_load_lds_dwordx4 v136, s[26:27]
	s_mov_b32 m0, s59
	v_lshl_add_u64 v[220:221], vcc, 0, v[134:135]
	global_load_lds_dwordx4 v132, s[60:61]
	s_add_i32 m0, s59, 0x2000
	s_nop 0
	global_load_lds_dwordx4 v136, s[60:61]
	v_lshl_add_u64 v[218:219], vcc, 0, v[130:131]
	s_mov_b32 m0, s23
	s_nop 0
	global_load_lds_dwordx4 v[218:219], off
	s_mov_b32 m0, s45
	s_nop 0
	global_load_lds_dwordx4 v[220:221], off
	s_waitcnt vmcnt(8)
	s_waitcnt lgkmcnt(0)
	s_barrier
	s_waitcnt lgkmcnt(0)
	v_mfma_f32_16x16x32_bf16 v[94:97], v[142:145], v[182:185], 0
	v_mfma_f32_16x16x32_bf16 v[94:97], v[146:149], v[186:189], v[94:97]
	v_mfma_f32_16x16x32_bf16 v[90:93], v[154:157], v[186:189], 0
	v_mfma_f32_16x16x32_bf16 v[90:93], v[150:153], v[182:185], v[90:93]
	v_mfma_f32_16x16x32_bf16 v[78:81], v[150:153], v[190:193], 0
	v_mfma_f32_16x16x32_bf16 v[78:81], v[154:157], v[194:197], v[78:81]
	v_mfma_f32_16x16x32_bf16 v[86:89], v[146:149], v[194:197], 0
	v_mfma_f32_16x16x32_bf16 v[86:89], v[142:145], v[190:193], v[86:89]
	v_mfma_f32_16x16x32_bf16 v[66:69], v[142:145], v[198:201], 0
	v_mfma_f32_16x16x32_bf16 v[66:69], v[146:149], v[202:205], v[66:69]
	v_mfma_f32_16x16x32_bf16 v[58:61], v[154:157], v[202:205], 0
	v_mfma_f32_16x16x32_bf16 v[58:61], v[150:153], v[198:201], v[58:61]
	v_mfma_f32_16x16x32_bf16 v[42:45], v[150:153], v[206:209], 0
	v_mfma_f32_16x16x32_bf16 v[42:45], v[154:157], v[210:213], v[42:45]
	v_mfma_f32_16x16x32_bf16 v[50:53], v[146:149], v[210:213], 0
	v_mfma_f32_16x16x32_bf16 v[50:53], v[142:145], v[206:209], v[50:53]
	v_mfma_f32_16x16x32_bf16 v[6:9], v[158:161], v[206:209], 0
	v_mfma_f32_16x16x32_bf16 v[6:9], v[162:165], v[210:213], v[6:9]
	v_mfma_f32_16x16x32_bf16 v[2:5], v[178:181], v[210:213], 0
	v_mfma_f32_16x16x32_bf16 v[2:5], v[174:177], v[206:209], v[2:5]
	v_mfma_f32_16x16x32_bf16 v[10:13], v[174:177], v[198:201], 0
	v_mfma_f32_16x16x32_bf16 v[10:13], v[178:181], v[202:205], v[10:13]
	v_mfma_f32_16x16x32_bf16 v[14:17], v[162:165], v[202:205], 0
	v_mfma_f32_16x16x32_bf16 v[14:17], v[158:161], v[198:201], v[14:17]
	v_mfma_f32_16x16x32_bf16 v[22:25], v[158:161], v[190:193], 0
	v_mfma_f32_16x16x32_bf16 v[22:25], v[162:165], v[194:197], v[22:25]
	v_mfma_f32_16x16x32_bf16 v[18:21], v[178:181], v[194:197], 0
	v_mfma_f32_16x16x32_bf16 v[18:21], v[174:177], v[190:193], v[18:21]
	v_mfma_f32_16x16x32_bf16 v[26:29], v[174:177], v[182:185], 0
	v_mfma_f32_16x16x32_bf16 v[26:29], v[178:181], v[186:189], v[26:29]
	v_mfma_f32_16x16x32_bf16 v[30:33], v[162:165], v[186:189], 0
	v_mfma_f32_16x16x32_bf16 v[30:33], v[158:161], v[182:185], v[30:33]
	s_barrier
	s_add_i32 s59, 0, 0x18000
	v_add_u32_e32 v0, s59, v167
	s_add_i32 s62, 0, 0x1c000
	ds_read_b128 v[142:145], v0
	ds_read_b128 v[146:149], v0 offset:1024
	ds_read_b128 v[150:153], v0 offset:2048
	ds_read_b128 v[154:157], v0 offset:3072
	v_add_u32_e32 v0, s62, v167
	ds_read_b128 v[158:161], v0
	ds_read_b128 v[162:165], v0 offset:1024
	ds_read_b128 v[174:177], v0 offset:2048
	ds_read_b128 v[178:181], v0 offset:3072
	s_add_u32 s60, vcc_lo, 0x40000
	s_addc_u32 s61, vcc_hi, 0
	s_mov_b32 m0, s47
	ds_read_b128 v[182:185], v173 offset:32768
	ds_read_b128 v[186:189], v173 offset:33792
	ds_read_b128 v[190:193], v173 offset:34816
	ds_read_b128 v[194:197], v173 offset:35840
	ds_read_b128 v[198:201], v173 offset:36864
	ds_read_b128 v[202:205], v173 offset:37888
	ds_read_b128 v[206:209], v173 offset:38912
	ds_read_b128 v[210:213], v173 offset:39936
	global_load_lds_dwordx4 v130, s[60:61]
	v_lshl_add_u64 v[222:223], s[60:61], 0, v[134:135]
	s_mov_b32 m0, s49
	s_nop 0
	global_load_lds_dwordx4 v[222:223], off
	s_waitcnt vmcnt(8)
	s_waitcnt lgkmcnt(0)
	s_barrier
	s_waitcnt lgkmcnt(0)
	v_mfma_f32_16x16x32_bf16 v[126:129], v[142:145], v[182:185], v[126:129]
	v_mfma_f32_16x16x32_bf16 v[126:129], v[146:149], v[186:189], v[126:129]
	v_mfma_f32_16x16x32_bf16 v[122:125], v[154:157], v[186:189], v[122:125]
	v_mfma_f32_16x16x32_bf16 v[122:125], v[150:153], v[182:185], v[122:125]
	v_mfma_f32_16x16x32_bf16 v[114:117], v[150:153], v[190:193], v[114:117]
	v_mfma_f32_16x16x32_bf16 v[114:117], v[154:157], v[194:197], v[114:117]
	v_mfma_f32_16x16x32_bf16 v[118:121], v[146:149], v[194:197], v[118:121]
	v_mfma_f32_16x16x32_bf16 v[118:121], v[142:145], v[190:193], v[118:121]
	v_mfma_f32_16x16x32_bf16 v[110:113], v[142:145], v[198:201], v[110:113]
	v_mfma_f32_16x16x32_bf16 v[110:113], v[146:149], v[202:205], v[110:113]
	v_mfma_f32_16x16x32_bf16 v[106:109], v[154:157], v[202:205], v[106:109]
	v_mfma_f32_16x16x32_bf16 v[106:109], v[150:153], v[198:201], v[106:109]
	v_mfma_f32_16x16x32_bf16 v[98:101], v[150:153], v[206:209], v[98:101]
	v_mfma_f32_16x16x32_bf16 v[98:101], v[154:157], v[210:213], v[98:101]
	v_mfma_f32_16x16x32_bf16 v[102:105], v[146:149], v[210:213], v[102:105]
	v_mfma_f32_16x16x32_bf16 v[102:105], v[142:145], v[206:209], v[102:105]
	v_mfma_f32_16x16x32_bf16 v[38:41], v[158:161], v[206:209], v[38:41]
	v_mfma_f32_16x16x32_bf16 v[38:41], v[162:165], v[210:213], v[38:41]
	v_mfma_f32_16x16x32_bf16 v[34:37], v[178:181], v[210:213], v[34:37]
	v_mfma_f32_16x16x32_bf16 v[34:37], v[174:177], v[206:209], v[34:37]
	v_mfma_f32_16x16x32_bf16 v[46:49], v[174:177], v[198:201], v[46:49]
	v_mfma_f32_16x16x32_bf16 v[46:49], v[178:181], v[202:205], v[46:49]
	v_mfma_f32_16x16x32_bf16 v[54:57], v[162:165], v[202:205], v[54:57]
	v_mfma_f32_16x16x32_bf16 v[54:57], v[158:161], v[198:201], v[54:57]
	v_mfma_f32_16x16x32_bf16 v[70:73], v[158:161], v[190:193], v[70:73]
	v_mfma_f32_16x16x32_bf16 v[70:73], v[162:165], v[194:197], v[70:73]
	v_mfma_f32_16x16x32_bf16 v[62:65], v[178:181], v[194:197], v[62:65]
	v_mfma_f32_16x16x32_bf16 v[62:65], v[174:177], v[190:193], v[62:65]
	v_mfma_f32_16x16x32_bf16 v[74:77], v[174:177], v[182:185], v[74:77]
	v_mfma_f32_16x16x32_bf16 v[74:77], v[178:181], v[186:189], v[74:77]
	v_mfma_f32_16x16x32_bf16 v[82:85], v[162:165], v[186:189], v[82:85]
	v_mfma_f32_16x16x32_bf16 v[82:85], v[158:161], v[182:185], v[82:85]
	s_barrier
	s_add_i32 s59, s59, s44
	s_mov_b32 m0, s59
	ds_read_b128 v[182:185], v173 offset:49152
	ds_read_b128 v[186:189], v173 offset:50176
	ds_read_b128 v[190:193], v173 offset:51200
	ds_read_b128 v[194:197], v173 offset:52224
	ds_read_b128 v[198:201], v173 offset:53248
	ds_read_b128 v[202:205], v173 offset:54272
	ds_read_b128 v[206:209], v173 offset:55296
	ds_read_b128 v[210:213], v173 offset:56320
	global_load_lds_dwordx4 v132, s[64:65]
	s_add_i32 m0, s59, 0x2000
	s_add_u32 s26, s26, 0x40080
	s_addc_u32 s27, s27, 0
	s_add_i32 s59, s62, s44
	global_load_lds_dwordx4 v136, s[64:65]
	s_mov_b32 m0, s59
	s_nop 0
	global_load_lds_dwordx4 v132, s[26:27]
	s_add_i32 m0, s59, 0x2000
	s_nop 0
	global_load_lds_dwordx4 v136, s[26:27]
	v_lshl_add_u64 v[214:215], v[218:219], 0, s[98:99]
	s_mov_b32 m0, s52
	s_nop 0
	global_load_lds_dwordx4 v[214:215], off
	v_lshl_add_u64 v[214:215], v[220:221], 0, s[98:99]
	s_mov_b32 m0, s53
	s_nop 0
	global_load_lds_dwordx4 v[214:215], off
	s_waitcnt vmcnt(8)
	s_waitcnt lgkmcnt(0)
	s_barrier
	s_waitcnt lgkmcnt(0)
	v_mfma_f32_16x16x32_bf16 v[94:97], v[142:145], v[182:185], v[94:97]
	v_mfma_f32_16x16x32_bf16 v[94:97], v[146:149], v[186:189], v[94:97]
	v_mfma_f32_16x16x32_bf16 v[90:93], v[154:157], v[186:189], v[90:93]
	v_mfma_f32_16x16x32_bf16 v[90:93], v[150:153], v[182:185], v[90:93]
	v_mfma_f32_16x16x32_bf16 v[78:81], v[150:153], v[190:193], v[78:81]
	v_mfma_f32_16x16x32_bf16 v[78:81], v[154:157], v[194:197], v[78:81]
	v_mfma_f32_16x16x32_bf16 v[86:89], v[146:149], v[194:197], v[86:89]
	v_mfma_f32_16x16x32_bf16 v[86:89], v[142:145], v[190:193], v[86:89]
	v_mfma_f32_16x16x32_bf16 v[66:69], v[142:145], v[198:201], v[66:69]
	v_mfma_f32_16x16x32_bf16 v[66:69], v[146:149], v[202:205], v[66:69]
	v_mfma_f32_16x16x32_bf16 v[58:61], v[154:157], v[202:205], v[58:61]
	v_mfma_f32_16x16x32_bf16 v[58:61], v[150:153], v[198:201], v[58:61]
	v_mfma_f32_16x16x32_bf16 v[42:45], v[150:153], v[206:209], v[42:45]
	v_mfma_f32_16x16x32_bf16 v[42:45], v[154:157], v[210:213], v[42:45]
	v_mfma_f32_16x16x32_bf16 v[50:53], v[146:149], v[210:213], v[50:53]
	v_mfma_f32_16x16x32_bf16 v[50:53], v[142:145], v[206:209], v[50:53]
	v_mfma_f32_16x16x32_bf16 v[6:9], v[158:161], v[206:209], v[6:9]
	v_mfma_f32_16x16x32_bf16 v[6:9], v[162:165], v[210:213], v[6:9]
	v_mfma_f32_16x16x32_bf16 v[2:5], v[178:181], v[210:213], v[2:5]
	v_mfma_f32_16x16x32_bf16 v[2:5], v[174:177], v[206:209], v[2:5]
	v_mfma_f32_16x16x32_bf16 v[10:13], v[174:177], v[198:201], v[10:13]
	v_mfma_f32_16x16x32_bf16 v[10:13], v[178:181], v[202:205], v[10:13]
	v_mfma_f32_16x16x32_bf16 v[14:17], v[162:165], v[202:205], v[14:17]
	v_mfma_f32_16x16x32_bf16 v[14:17], v[158:161], v[198:201], v[14:17]
	v_mfma_f32_16x16x32_bf16 v[22:25], v[158:161], v[190:193], v[22:25]
	v_mfma_f32_16x16x32_bf16 v[22:25], v[162:165], v[194:197], v[22:25]
	v_mfma_f32_16x16x32_bf16 v[18:21], v[178:181], v[194:197], v[18:21]
	v_mfma_f32_16x16x32_bf16 v[18:21], v[174:177], v[190:193], v[18:21]
	v_mfma_f32_16x16x32_bf16 v[26:29], v[174:177], v[182:185], v[26:29]
	v_mfma_f32_16x16x32_bf16 v[26:29], v[178:181], v[186:189], v[26:29]
	v_mfma_f32_16x16x32_bf16 v[30:33], v[162:165], v[186:189], v[30:33]
	v_mfma_f32_16x16x32_bf16 v[30:33], v[158:161], v[182:185], v[30:33]
	s_barrier
	s_add_i32 s58, s58, 2
	s_add_u32 s40, s40, 0x100
	s_addc_u32 s41, s41, 0
	s_add_u32 s56, s56, 0x100
	s_addc_u32 s57, s57, 0
	s_cmp_gt_u32 s58, 13
	s_cbranch_scc1 .Lpeel_done_160
.LBB0_160:
	s_add_u32 s26, s40, 0xfffc0080
	s_addc_u32 s27, s41, -1
	s_add_i32 s59, 0, 0x10000
	s_cmp_eq_u32 s58, 12
	s_cselect_b32 vcc_hi, s29, s27
	s_cselect_b32 vcc_lo, s43, s26
	v_add_u32_e32 v0, s59, v167
	s_cselect_b32 s27, s21, s57
	s_cselect_b32 s26, s55, s56
	s_add_i32 s62, 0, 0x14000
	ds_read_b128 v[142:145], v0
	ds_read_b128 v[146:149], v0 offset:1024
	ds_read_b128 v[150:153], v0 offset:2048
	ds_read_b128 v[154:157], v0 offset:3072
	v_add_u32_e32 v0, s62, v167
	ds_read_b128 v[158:161], v0
	ds_read_b128 v[162:165], v0 offset:1024
	ds_read_b128 v[174:177], v0 offset:2048
	ds_read_b128 v[178:181], v0 offset:3072
	s_add_i32 m0, s23, 0xc000
	ds_read_b128 v[182:185], v173
	ds_read_b128 v[186:189], v173 offset:1024
	ds_read_b128 v[190:193], v173 offset:2048
	ds_read_b128 v[194:197], v173 offset:3072
	ds_read_b128 v[198:201], v173 offset:4096
	ds_read_b128 v[202:205], v173 offset:5120
	ds_read_b128 v[206:209], v173 offset:6144
	ds_read_b128 v[210:213], v173 offset:7168
	global_load_lds_dwordx4 v138, s[40:41]
	s_add_i32 m0, s23, 0xe000
	s_nop 0
	global_load_lds_dwordx4 v140, s[40:41]
	s_waitcnt vmcnt(8)
	s_waitcnt lgkmcnt(0)
	s_barrier
	s_waitcnt lgkmcnt(0)
	v_mfma_f32_16x16x32_bf16 v[126:129], v[142:145], v[182:185], v[126:129]
	v_mfma_f32_16x16x32_bf16 v[126:129], v[146:149], v[186:189], v[126:129]
	v_mfma_f32_16x16x32_bf16 v[122:125], v[154:157], v[186:189], v[122:125]
	v_mfma_f32_16x16x32_bf16 v[122:125], v[150:153], v[182:185], v[122:125]
	v_mfma_f32_16x16x32_bf16 v[114:117], v[150:153], v[190:193], v[114:117]
	v_mfma_f32_16x16x32_bf16 v[114:117], v[154:157], v[194:197], v[114:117]
	v_mfma_f32_16x16x32_bf16 v[118:121], v[146:149], v[194:197], v[118:121]
	v_mfma_f32_16x16x32_bf16 v[118:121], v[142:145], v[190:193], v[118:121]
	v_mfma_f32_16x16x32_bf16 v[110:113], v[142:145], v[198:201], v[110:113]
	v_mfma_f32_16x16x32_bf16 v[110:113], v[146:149], v[202:205], v[110:113]
	v_mfma_f32_16x16x32_bf16 v[106:109], v[154:157], v[202:205], v[106:109]
	v_mfma_f32_16x16x32_bf16 v[106:109], v[150:153], v[198:201], v[106:109]
	v_mfma_f32_16x16x32_bf16 v[98:101], v[150:153], v[206:209], v[98:101]
	v_mfma_f32_16x16x32_bf16 v[98:101], v[154:157], v[210:213], v[98:101]
	v_mfma_f32_16x16x32_bf16 v[102:105], v[146:149], v[210:213], v[102:105]
	v_mfma_f32_16x16x32_bf16 v[102:105], v[142:145], v[206:209], v[102:105]
	v_mfma_f32_16x16x32_bf16 v[38:41], v[158:161], v[206:209], v[38:41]
	v_mfma_f32_16x16x32_bf16 v[38:41], v[162:165], v[210:213], v[38:41]
	v_mfma_f32_16x16x32_bf16 v[34:37], v[178:181], v[210:213], v[34:37]
	v_mfma_f32_16x16x32_bf16 v[34:37], v[174:177], v[206:209], v[34:37]
	v_mfma_f32_16x16x32_bf16 v[46:49], v[174:177], v[198:201], v[46:49]
	v_mfma_f32_16x16x32_bf16 v[46:49], v[178:181], v[202:205], v[46:49]
	v_mfma_f32_16x16x32_bf16 v[54:57], v[162:165], v[202:205], v[54:57]
	v_mfma_f32_16x16x32_bf16 v[54:57], v[158:161], v[198:201], v[54:57]
	v_mfma_f32_16x16x32_bf16 v[70:73], v[158:161], v[190:193], v[70:73]
	v_mfma_f32_16x16x32_bf16 v[70:73], v[162:165], v[194:197], v[70:73]
	v_mfma_f32_16x16x32_bf16 v[62:65], v[178:181], v[194:197], v[62:65]
	v_mfma_f32_16x16x32_bf16 v[62:65], v[174:177], v[190:193], v[62:65]
	v_mfma_f32_16x16x32_bf16 v[74:77], v[174:177], v[182:185], v[74:77]
	v_mfma_f32_16x16x32_bf16 v[74:77], v[178:181], v[186:189], v[74:77]
	v_mfma_f32_16x16x32_bf16 v[82:85], v[162:165], v[186:189], v[82:85]
	v_mfma_f32_16x16x32_bf16 v[82:85], v[158:161], v[182:185], v[82:85]
	s_barrier
	s_add_i32 s59, s59, s44
	s_add_u32 s64, s26, s98
	s_addc_u32 s65, s27, s99
	s_mov_b32 m0, s59
	ds_read_b128 v[182:185], v173 offset:16384
	ds_read_b128 v[186:189], v173 offset:17408
	ds_read_b128 v[190:193], v173 offset:18432
	ds_read_b128 v[194:197], v173 offset:19456
	ds_read_b128 v[198:201], v173 offset:20480
	ds_read_b128 v[202:205], v173 offset:21504
	ds_read_b128 v[206:209], v173 offset:22528
	ds_read_b128 v[210:213], v173 offset:23552
	global_load_lds_dwordx4 v132, s[26:27]
	s_add_i32 m0, s59, 0x2000
	s_add_u32 s60, s26, 0x40000
	s_addc_u32 s61, s27, 0
	s_add_i32 s59, s62, s44
	global_load_lds_dwordx4 v136, s[26:27]
	s_mov_b32 m0, s59
	v_lshl_add_u64 v[220:221], vcc, 0, v[134:135]
	global_load_lds_dwordx4 v132, s[60:61]
	s_add_i32 m0, s59, 0x2000
	s_nop 0
	global_load_lds_dwordx4 v136, s[60:61]
	v_lshl_add_u64 v[218:219], vcc, 0, v[130:131]
	s_mov_b32 m0, s23
	s_nop 0
	global_load_lds_dwordx4 v[218:219], off
	s_mov_b32 m0, s45
	s_nop 0
	global_load_lds_dwordx4 v[220:221], off
	s_waitcnt vmcnt(8)
	s_waitcnt lgkmcnt(0)
	s_barrier
	s_waitcnt lgkmcnt(0)
	v_mfma_f32_16x16x32_bf16 v[94:97], v[142:145], v[182:185], v[94:97]
	v_mfma_f32_16x16x32_bf16 v[94:97], v[146:149], v[186:189], v[94:97]
	v_mfma_f32_16x16x32_bf16 v[90:93], v[154:157], v[186:189], v[90:93]
	v_mfma_f32_16x16x32_bf16 v[90:93], v[150:153], v[182:185], v[90:93]
	v_mfma_f32_16x16x32_bf16 v[78:81], v[150:153], v[190:193], v[78:81]
	v_mfma_f32_16x16x32_bf16 v[78:81], v[154:157], v[194:197], v[78:81]
	v_mfma_f32_16x16x32_bf16 v[86:89], v[146:149], v[194:197], v[86:89]
	v_mfma_f32_16x16x32_bf16 v[86:89], v[142:145], v[190:193], v[86:89]
	v_mfma_f32_16x16x32_bf16 v[66:69], v[142:145], v[198:201], v[66:69]
	v_mfma_f32_16x16x32_bf16 v[66:69], v[146:149], v[202:205], v[66:69]
	v_mfma_f32_16x16x32_bf16 v[58:61], v[154:157], v[202:205], v[58:61]
	v_mfma_f32_16x16x32_bf16 v[58:61], v[150:153], v[198:201], v[58:61]
	v_mfma_f32_16x16x32_bf16 v[42:45], v[150:153], v[206:209], v[42:45]
	v_mfma_f32_16x16x32_bf16 v[42:45], v[154:157], v[210:213], v[42:45]
	v_mfma_f32_16x16x32_bf16 v[50:53], v[146:149], v[210:213], v[50:53]
	v_mfma_f32_16x16x32_bf16 v[50:53], v[142:145], v[206:209], v[50:53]
	v_mfma_f32_16x16x32_bf16 v[6:9], v[158:161], v[206:209], v[6:9]
	v_mfma_f32_16x16x32_bf16 v[6:9], v[162:165], v[210:213], v[6:9]
	v_mfma_f32_16x16x32_bf16 v[2:5], v[178:181], v[210:213], v[2:5]
	v_mfma_f32_16x16x32_bf16 v[2:5], v[174:177], v[206:209], v[2:5]
	v_mfma_f32_16x16x32_bf16 v[10:13], v[174:177], v[198:201], v[10:13]
	v_mfma_f32_16x16x32_bf16 v[10:13], v[178:181], v[202:205], v[10:13]
	v_mfma_f32_16x16x32_bf16 v[14:17], v[162:165], v[202:205], v[14:17]
	v_mfma_f32_16x16x32_bf16 v[14:17], v[158:161], v[198:201], v[14:17]
	v_mfma_f32_16x16x32_bf16 v[22:25], v[158:161], v[190:193], v[22:25]
	v_mfma_f32_16x16x32_bf16 v[22:25], v[162:165], v[194:197], v[22:25]
	v_mfma_f32_16x16x32_bf16 v[18:21], v[178:181], v[194:197], v[18:21]
	v_mfma_f32_16x16x32_bf16 v[18:21], v[174:177], v[190:193], v[18:21]
	v_mfma_f32_16x16x32_bf16 v[26:29], v[174:177], v[182:185], v[26:29]
	v_mfma_f32_16x16x32_bf16 v[26:29], v[178:181], v[186:189], v[26:29]
	v_mfma_f32_16x16x32_bf16 v[30:33], v[162:165], v[186:189], v[30:33]
	v_mfma_f32_16x16x32_bf16 v[30:33], v[158:161], v[182:185], v[30:33]
	s_barrier
	s_add_i32 s59, 0, 0x18000
	v_add_u32_e32 v0, s59, v167
	s_add_i32 s62, 0, 0x1c000
	ds_read_b128 v[142:145], v0
	ds_read_b128 v[146:149], v0 offset:1024
	ds_read_b128 v[150:153], v0 offset:2048
	ds_read_b128 v[154:157], v0 offset:3072
	v_add_u32_e32 v0, s62, v167
	ds_read_b128 v[158:161], v0
	ds_read_b128 v[162:165], v0 offset:1024
	ds_read_b128 v[174:177], v0 offset:2048
	ds_read_b128 v[178:181], v0 offset:3072
	s_add_u32 s60, vcc_lo, 0x40000
	s_addc_u32 s61, vcc_hi, 0
	s_mov_b32 m0, s47
	ds_read_b128 v[182:185], v173 offset:32768
	ds_read_b128 v[186:189], v173 offset:33792
	ds_read_b128 v[190:193], v173 offset:34816
	ds_read_b128 v[194:197], v173 offset:35840
	ds_read_b128 v[198:201], v173 offset:36864
	ds_read_b128 v[202:205], v173 offset:37888
	ds_read_b128 v[206:209], v173 offset:38912
	ds_read_b128 v[210:213], v173 offset:39936
	global_load_lds_dwordx4 v130, s[60:61]
	s_mov_b32 m0, s49
	s_nop 0
	global_load_lds_dwordx4 v134, s[60:61]
	s_waitcnt vmcnt(8)
	s_waitcnt lgkmcnt(0)
	s_barrier
	s_waitcnt lgkmcnt(0)
	v_mfma_f32_16x16x32_bf16 v[126:129], v[142:145], v[182:185], v[126:129]
	v_mfma_f32_16x16x32_bf16 v[126:129], v[146:149], v[186:189], v[126:129]
	v_mfma_f32_16x16x32_bf16 v[122:125], v[154:157], v[186:189], v[122:125]
	v_mfma_f32_16x16x32_bf16 v[122:125], v[150:153], v[182:185], v[122:125]
	v_mfma_f32_16x16x32_bf16 v[114:117], v[150:153], v[190:193], v[114:117]
	v_mfma_f32_16x16x32_bf16 v[114:117], v[154:157], v[194:197], v[114:117]
	v_mfma_f32_16x16x32_bf16 v[118:121], v[146:149], v[194:197], v[118:121]
	v_mfma_f32_16x16x32_bf16 v[118:121], v[142:145], v[190:193], v[118:121]
	v_mfma_f32_16x16x32_bf16 v[110:113], v[142:145], v[198:201], v[110:113]
	v_mfma_f32_16x16x32_bf16 v[110:113], v[146:149], v[202:205], v[110:113]
	v_mfma_f32_16x16x32_bf16 v[106:109], v[154:157], v[202:205], v[106:109]
	v_mfma_f32_16x16x32_bf16 v[106:109], v[150:153], v[198:201], v[106:109]
	v_mfma_f32_16x16x32_bf16 v[98:101], v[150:153], v[206:209], v[98:101]
	v_mfma_f32_16x16x32_bf16 v[98:101], v[154:157], v[210:213], v[98:101]
	v_mfma_f32_16x16x32_bf16 v[102:105], v[146:149], v[210:213], v[102:105]
	v_mfma_f32_16x16x32_bf16 v[102:105], v[142:145], v[206:209], v[102:105]
	v_mfma_f32_16x16x32_bf16 v[38:41], v[158:161], v[206:209], v[38:41]
	v_mfma_f32_16x16x32_bf16 v[38:41], v[162:165], v[210:213], v[38:41]
	v_mfma_f32_16x16x32_bf16 v[34:37], v[178:181], v[210:213], v[34:37]
	v_mfma_f32_16x16x32_bf16 v[34:37], v[174:177], v[206:209], v[34:37]
	v_mfma_f32_16x16x32_bf16 v[46:49], v[174:177], v[198:201], v[46:49]
	v_mfma_f32_16x16x32_bf16 v[46:49], v[178:181], v[202:205], v[46:49]
	v_mfma_f32_16x16x32_bf16 v[54:57], v[162:165], v[202:205], v[54:57]
	v_mfma_f32_16x16x32_bf16 v[54:57], v[158:161], v[198:201], v[54:57]
	v_mfma_f32_16x16x32_bf16 v[70:73], v[158:161], v[190:193], v[70:73]
	v_mfma_f32_16x16x32_bf16 v[70:73], v[162:165], v[194:197], v[70:73]
	v_mfma_f32_16x16x32_bf16 v[62:65], v[178:181], v[194:197], v[62:65]
	v_mfma_f32_16x16x32_bf16 v[62:65], v[174:177], v[190:193], v[62:65]
	v_mfma_f32_16x16x32_bf16 v[74:77], v[174:177], v[182:185], v[74:77]
	v_mfma_f32_16x16x32_bf16 v[74:77], v[178:181], v[186:189], v[74:77]
	v_mfma_f32_16x16x32_bf16 v[82:85], v[162:165], v[186:189], v[82:85]
	v_mfma_f32_16x16x32_bf16 v[82:85], v[158:161], v[182:185], v[82:85]
	s_barrier
	s_add_i32 s59, s59, s44
	s_mov_b32 m0, s59
	ds_read_b128 v[182:185], v173 offset:49152
	ds_read_b128 v[186:189], v173 offset:50176
	ds_read_b128 v[190:193], v173 offset:51200
	ds_read_b128 v[194:197], v173 offset:52224
	ds_read_b128 v[198:201], v173 offset:53248
	ds_read_b128 v[202:205], v173 offset:54272
	ds_read_b128 v[206:209], v173 offset:55296
	ds_read_b128 v[210:213], v173 offset:56320
	global_load_lds_dwordx4 v132, s[64:65]
	s_add_i32 m0, s59, 0x2000
	s_add_u32 s26, s26, 0x40080
	s_addc_u32 s27, s27, 0
	s_add_i32 s59, s62, s44
	global_load_lds_dwordx4 v136, s[64:65]
	s_mov_b32 m0, s59
	s_nop 0
	global_load_lds_dwordx4 v132, s[26:27]
	s_add_i32 m0, s59, 0x2000
	s_nop 0
	global_load_lds_dwordx4 v136, s[26:27]
	v_lshl_add_u64 v[214:215], v[218:219], 0, s[98:99]
	s_mov_b32 m0, s52
	s_nop 0
	global_load_lds_dwordx4 v[214:215], off
	v_lshl_add_u64 v[214:215], v[220:221], 0, s[98:99]
	s_mov_b32 m0, s53
	s_nop 0
	global_load_lds_dwordx4 v[214:215], off
	s_waitcnt vmcnt(8)
	s_waitcnt lgkmcnt(0)
	s_barrier
	s_waitcnt lgkmcnt(0)
	v_mfma_f32_16x16x32_bf16 v[94:97], v[142:145], v[182:185], v[94:97]
	v_mfma_f32_16x16x32_bf16 v[94:97], v[146:149], v[186:189], v[94:97]
	v_mfma_f32_16x16x32_bf16 v[90:93], v[154:157], v[186:189], v[90:93]
	v_mfma_f32_16x16x32_bf16 v[90:93], v[150:153], v[182:185], v[90:93]
	v_mfma_f32_16x16x32_bf16 v[78:81], v[150:153], v[190:193], v[78:81]
	v_mfma_f32_16x16x32_bf16 v[78:81], v[154:157], v[194:197], v[78:81]
	v_mfma_f32_16x16x32_bf16 v[86:89], v[146:149], v[194:197], v[86:89]
	v_mfma_f32_16x16x32_bf16 v[86:89], v[142:145], v[190:193], v[86:89]
	v_mfma_f32_16x16x32_bf16 v[66:69], v[142:145], v[198:201], v[66:69]
	v_mfma_f32_16x16x32_bf16 v[66:69], v[146:149], v[202:205], v[66:69]
	v_mfma_f32_16x16x32_bf16 v[58:61], v[154:157], v[202:205], v[58:61]
	v_mfma_f32_16x16x32_bf16 v[58:61], v[150:153], v[198:201], v[58:61]
	v_mfma_f32_16x16x32_bf16 v[42:45], v[150:153], v[206:209], v[42:45]
	v_mfma_f32_16x16x32_bf16 v[42:45], v[154:157], v[210:213], v[42:45]
	v_mfma_f32_16x16x32_bf16 v[50:53], v[146:149], v[210:213], v[50:53]
	v_mfma_f32_16x16x32_bf16 v[50:53], v[142:145], v[206:209], v[50:53]
	v_mfma_f32_16x16x32_bf16 v[6:9], v[158:161], v[206:209], v[6:9]
	v_mfma_f32_16x16x32_bf16 v[6:9], v[162:165], v[210:213], v[6:9]
	v_mfma_f32_16x16x32_bf16 v[2:5], v[178:181], v[210:213], v[2:5]
	v_mfma_f32_16x16x32_bf16 v[2:5], v[174:177], v[206:209], v[2:5]
	v_mfma_f32_16x16x32_bf16 v[10:13], v[174:177], v[198:201], v[10:13]
	v_mfma_f32_16x16x32_bf16 v[10:13], v[178:181], v[202:205], v[10:13]
	v_mfma_f32_16x16x32_bf16 v[14:17], v[162:165], v[202:205], v[14:17]
	v_mfma_f32_16x16x32_bf16 v[14:17], v[158:161], v[198:201], v[14:17]
	v_mfma_f32_16x16x32_bf16 v[22:25], v[158:161], v[190:193], v[22:25]
	v_mfma_f32_16x16x32_bf16 v[22:25], v[162:165], v[194:197], v[22:25]
	v_mfma_f32_16x16x32_bf16 v[18:21], v[178:181], v[194:197], v[18:21]
	v_mfma_f32_16x16x32_bf16 v[18:21], v[174:177], v[190:193], v[18:21]
	v_mfma_f32_16x16x32_bf16 v[26:29], v[174:177], v[182:185], v[26:29]
	v_mfma_f32_16x16x32_bf16 v[26:29], v[178:181], v[186:189], v[26:29]
	v_mfma_f32_16x16x32_bf16 v[30:33], v[162:165], v[186:189], v[30:33]
	v_mfma_f32_16x16x32_bf16 v[30:33], v[158:161], v[182:185], v[30:33]
	s_barrier
	s_add_i32 s58, s58, 2
	s_add_u32 s40, s40, 0x100
	s_addc_u32 s41, s41, 0
	s_add_u32 s56, s56, 0x100
	s_addc_u32 s57, s57, 0
	s_cmp_gt_u32 s58, 13
	s_cbranch_scc0 .LBB0_160

.LBB0_216:
	s_add_i32 s13, s61, -2
	s_add_u32 s28, s28, 0x80
	s_addc_u32 s29, s29, 0
	s_add_u32 s23, s40, 0x100
	s_addc_u32 s40, s41, 0
	s_mov_b32 s30, 0
	s_add_i32 s41, s30, 2
	s_add_u32 vcc_lo, s28, 0x80
	s_addc_u32 s31, s29, 0
	s_add_i32 s62, 0, 0x10000
	s_cmp_eq_u32 s13, s30
	s_cselect_b32 s31, s25, s31
	s_cselect_b32 s30, s24, vcc_lo
	v_add_u32_e32 v145, s62, v175
	s_cselect_b32 vcc_hi, s27, s40
	s_cselect_b32 vcc_lo, s26, s23
	s_add_i32 s63, 0, 0x14000
	ds_read_b128 v[130:133], v145
	ds_read_b128 v[134:137], v145 offset:1024
	ds_read_b128 v[152:155], v145 offset:2048
	ds_read_b128 v[156:159], v145 offset:3072
	v_add_u32_e32 v145, s63, v175
	ds_read_b128 v[160:163], v145
	ds_read_b128 v[164:167], v145 offset:1024
	ds_read_b128 v[168:171], v145 offset:2048
	ds_read_b128 v[186:189], v145 offset:3072
	v_lshl_add_u64 v[172:173], s[28:29], 0, v[148:149]
	s_add_i32 m0, s93, 0xc000
	ds_read_b128 v[190:193], v184
	ds_read_b128 v[194:197], v184 offset:1024
	ds_read_b128 v[198:201], v184 offset:2048
	ds_read_b128 v[202:205], v184 offset:3072
	ds_read_b128 v[206:209], v184 offset:4096
	ds_read_b128 v[210:213], v184 offset:5120
	ds_read_b128 v[214:217], v184 offset:6144
	ds_read_b128 v[218:221], v184 offset:7168
	global_load_lds_dwordx4 v[172:173], off
	v_lshl_add_u64 v[172:173], s[28:29], 0, v[150:151]
	s_add_i32 m0, s93, 0xe000
	s_nop 0
	global_load_lds_dwordx4 v[172:173], off
	s_waitcnt vmcnt(8)
	s_waitcnt lgkmcnt(0)
	s_barrier
	s_waitcnt lgkmcnt(0)
	v_mfma_f32_16x16x32_bf16 v[126:129], v[130:133], v[190:193], 0
	v_mfma_f32_16x16x32_bf16 v[126:129], v[134:137], v[194:197], v[126:129]
	v_mfma_f32_16x16x32_bf16 v[122:125], v[156:159], v[194:197], 0
	v_mfma_f32_16x16x32_bf16 v[122:125], v[152:155], v[190:193], v[122:125]
	v_mfma_f32_16x16x32_bf16 v[106:109], v[152:155], v[198:201], 0
	v_mfma_f32_16x16x32_bf16 v[106:109], v[156:159], v[202:205], v[106:109]
	v_mfma_f32_16x16x32_bf16 v[110:113], v[134:137], v[202:205], 0
	v_mfma_f32_16x16x32_bf16 v[110:113], v[130:133], v[198:201], v[110:113]
	v_mfma_f32_16x16x32_bf16 v[94:97], v[130:133], v[206:209], 0
	v_mfma_f32_16x16x32_bf16 v[94:97], v[134:137], v[210:213], v[94:97]
	v_mfma_f32_16x16x32_bf16 v[90:93], v[156:159], v[210:213], 0
	v_mfma_f32_16x16x32_bf16 v[90:93], v[152:155], v[206:209], v[90:93]
	v_mfma_f32_16x16x32_bf16 v[74:77], v[152:155], v[214:217], 0
	v_mfma_f32_16x16x32_bf16 v[74:77], v[156:159], v[218:221], v[74:77]
	v_mfma_f32_16x16x32_bf16 v[78:81], v[134:137], v[218:221], 0
	v_mfma_f32_16x16x32_bf16 v[78:81], v[130:133], v[214:217], v[78:81]
	v_mfma_f32_16x16x32_bf16 v[70:73], v[160:163], v[214:217], 0
	v_mfma_f32_16x16x32_bf16 v[70:73], v[164:167], v[218:221], v[70:73]
	v_mfma_f32_16x16x32_bf16 v[66:69], v[186:189], v[218:221], 0
	v_mfma_f32_16x16x32_bf16 v[66:69], v[168:171], v[214:217], v[66:69]
	v_mfma_f32_16x16x32_bf16 v[82:85], v[168:171], v[206:209], 0
	v_mfma_f32_16x16x32_bf16 v[82:85], v[186:189], v[210:213], v[82:85]
	v_mfma_f32_16x16x32_bf16 v[86:89], v[164:167], v[210:213], 0
	v_mfma_f32_16x16x32_bf16 v[86:89], v[160:163], v[206:209], v[86:89]
	v_mfma_f32_16x16x32_bf16 v[102:105], v[160:163], v[198:201], 0
	v_mfma_f32_16x16x32_bf16 v[102:105], v[164:167], v[202:205], v[102:105]
	v_mfma_f32_16x16x32_bf16 v[98:101], v[186:189], v[202:205], 0
	v_mfma_f32_16x16x32_bf16 v[98:101], v[168:171], v[198:201], v[98:101]
	v_mfma_f32_16x16x32_bf16 v[114:117], v[168:171], v[190:193], 0
	v_mfma_f32_16x16x32_bf16 v[114:117], v[186:189], v[194:197], v[114:117]
	v_mfma_f32_16x16x32_bf16 v[118:121], v[164:167], v[194:197], 0
	v_mfma_f32_16x16x32_bf16 v[118:121], v[160:163], v[190:193], v[118:121]
	s_barrier
	s_add_i32 s62, s62, s49
	v_lshl_add_u64 v[172:173], vcc, 0, v[0:1]
	s_mov_b32 m0, s62
	ds_read_b128 v[190:193], v184 offset:16384
	ds_read_b128 v[194:197], v184 offset:17408
	ds_read_b128 v[198:201], v184 offset:18432
	ds_read_b128 v[202:205], v184 offset:19456
	ds_read_b128 v[206:209], v184 offset:20480
	ds_read_b128 v[210:213], v184 offset:21504
	ds_read_b128 v[214:217], v184 offset:22528
	ds_read_b128 v[218:221], v184 offset:23552
	global_load_lds_dwordx4 v[172:173], off
	s_add_i32 m0, s62, 0x2000
	v_lshl_add_u64 v[222:223], vcc, 0, v[142:143]
	s_add_u32 vcc_lo, vcc_lo, s96
	s_addc_u32 vcc_hi, vcc_hi, 0
	s_add_i32 s62, s63, s49
	global_load_lds_dwordx4 v[222:223], off
	v_lshl_add_u64 v[236:237], vcc, 0, v[0:1]
	s_mov_b32 m0, s62
	v_lshl_add_u64 v[238:239], vcc, 0, v[142:143]
	global_load_lds_dwordx4 v[236:237], off
	s_add_i32 m0, s62, 0x2000
	s_add_u32 s64, s30, s98
	s_addc_u32 s65, s31, s99
	global_load_lds_dwordx4 v[238:239], off
	s_mov_b32 m0, s93
	global_load_lds_dwordx4 v138, s[30:31]
	s_mov_b32 m0, s88
	s_nop 0
	global_load_lds_dwordx4 v140, s[30:31]
	s_waitcnt vmcnt(8)
	s_waitcnt lgkmcnt(0)
	s_barrier
	s_waitcnt lgkmcnt(0)
	v_mfma_f32_16x16x32_bf16 v[62:65], v[130:133], v[190:193], 0
	v_mfma_f32_16x16x32_bf16 v[62:65], v[134:137], v[194:197], v[62:65]
	v_mfma_f32_16x16x32_bf16 v[58:61], v[156:159], v[194:197], 0
	v_mfma_f32_16x16x32_bf16 v[58:61], v[152:155], v[190:193], v[58:61]
	v_mfma_f32_16x16x32_bf16 v[42:45], v[152:155], v[198:201], 0
	v_mfma_f32_16x16x32_bf16 v[42:45], v[156:159], v[202:205], v[42:45]
	v_mfma_f32_16x16x32_bf16 v[46:49], v[134:137], v[202:205], 0
	v_mfma_f32_16x16x32_bf16 v[46:49], v[130:133], v[198:201], v[46:49]
	v_mfma_f32_16x16x32_bf16 v[30:33], v[130:133], v[206:209], 0
	v_mfma_f32_16x16x32_bf16 v[30:33], v[134:137], v[210:213], v[30:33]
	v_mfma_f32_16x16x32_bf16 v[26:29], v[156:159], v[210:213], 0
	v_mfma_f32_16x16x32_bf16 v[26:29], v[152:155], v[206:209], v[26:29]
	v_mfma_f32_16x16x32_bf16 v[10:13], v[152:155], v[214:217], 0
	v_mfma_f32_16x16x32_bf16 v[10:13], v[156:159], v[218:221], v[10:13]
	v_mfma_f32_16x16x32_bf16 v[14:17], v[134:137], v[218:221], 0
	v_mfma_f32_16x16x32_bf16 v[14:17], v[130:133], v[214:217], v[14:17]
	v_mfma_f32_16x16x32_bf16 v[6:9], v[160:163], v[214:217], 0
	v_mfma_f32_16x16x32_bf16 v[6:9], v[164:167], v[218:221], v[6:9]
	v_mfma_f32_16x16x32_bf16 v[2:5], v[186:189], v[218:221], 0
	v_mfma_f32_16x16x32_bf16 v[2:5], v[168:171], v[214:217], v[2:5]
	v_mfma_f32_16x16x32_bf16 v[18:21], v[168:171], v[206:209], 0
	v_mfma_f32_16x16x32_bf16 v[18:21], v[186:189], v[210:213], v[18:21]
	v_mfma_f32_16x16x32_bf16 v[22:25], v[164:167], v[210:213], 0
	v_mfma_f32_16x16x32_bf16 v[22:25], v[160:163], v[206:209], v[22:25]
	v_mfma_f32_16x16x32_bf16 v[38:41], v[160:163], v[198:201], 0
	v_mfma_f32_16x16x32_bf16 v[38:41], v[164:167], v[202:205], v[38:41]
	v_mfma_f32_16x16x32_bf16 v[34:37], v[186:189], v[202:205], 0
	v_mfma_f32_16x16x32_bf16 v[34:37], v[168:171], v[198:201], v[34:37]
	v_mfma_f32_16x16x32_bf16 v[50:53], v[168:171], v[190:193], 0
	v_mfma_f32_16x16x32_bf16 v[50:53], v[186:189], v[194:197], v[50:53]
	v_mfma_f32_16x16x32_bf16 v[54:57], v[164:167], v[194:197], 0
	v_mfma_f32_16x16x32_bf16 v[54:57], v[160:163], v[190:193], v[54:57]
	s_barrier
	s_add_i32 s62, 0, 0x18000
	v_add_u32_e32 v145, s62, v175
	s_add_i32 s63, 0, 0x1c000
	ds_read_b128 v[130:133], v145
	ds_read_b128 v[134:137], v145 offset:1024
	ds_read_b128 v[152:155], v145 offset:2048
	ds_read_b128 v[156:159], v145 offset:3072
	v_add_u32_e32 v145, s63, v175
	ds_read_b128 v[160:163], v145
	ds_read_b128 v[164:167], v145 offset:1024
	ds_read_b128 v[168:171], v145 offset:2048
	ds_read_b128 v[186:189], v145 offset:3072
	s_add_u32 s30, s30, s96
	s_addc_u32 s31, s31, 0
	s_mov_b32 m0, s89
	ds_read_b128 v[190:193], v184 offset:32768
	ds_read_b128 v[194:197], v184 offset:33792
	ds_read_b128 v[198:201], v184 offset:34816
	ds_read_b128 v[202:205], v184 offset:35840
	ds_read_b128 v[206:209], v184 offset:36864
	ds_read_b128 v[210:213], v184 offset:37888
	ds_read_b128 v[214:217], v184 offset:38912
	ds_read_b128 v[218:221], v184 offset:39936
	global_load_lds_dwordx4 v138, s[30:31]
	v_lshl_add_u64 v[244:245], s[30:31], 0, v[140:141]
	s_mov_b32 m0, s52
	s_nop 0
	global_load_lds_dwordx4 v[244:245], off
	s_waitcnt vmcnt(8)
	s_waitcnt lgkmcnt(0)
	s_barrier
	s_waitcnt lgkmcnt(0)
	v_mfma_f32_16x16x32_bf16 v[126:129], v[130:133], v[190:193], v[126:129]
	v_mfma_f32_16x16x32_bf16 v[126:129], v[134:137], v[194:197], v[126:129]
	v_mfma_f32_16x16x32_bf16 v[122:125], v[156:159], v[194:197], v[122:125]
	v_mfma_f32_16x16x32_bf16 v[122:125], v[152:155], v[190:193], v[122:125]
	v_mfma_f32_16x16x32_bf16 v[106:109], v[152:155], v[198:201], v[106:109]
	v_mfma_f32_16x16x32_bf16 v[106:109], v[156:159], v[202:205], v[106:109]
	v_mfma_f32_16x16x32_bf16 v[110:113], v[134:137], v[202:205], v[110:113]
	v_mfma_f32_16x16x32_bf16 v[110:113], v[130:133], v[198:201], v[110:113]
	v_mfma_f32_16x16x32_bf16 v[94:97], v[130:133], v[206:209], v[94:97]
	v_mfma_f32_16x16x32_bf16 v[94:97], v[134:137], v[210:213], v[94:97]
	v_mfma_f32_16x16x32_bf16 v[90:93], v[156:159], v[210:213], v[90:93]
	v_mfma_f32_16x16x32_bf16 v[90:93], v[152:155], v[206:209], v[90:93]
	v_mfma_f32_16x16x32_bf16 v[74:77], v[152:155], v[214:217], v[74:77]
	v_mfma_f32_16x16x32_bf16 v[74:77], v[156:159], v[218:221], v[74:77]
	v_mfma_f32_16x16x32_bf16 v[78:81], v[134:137], v[218:221], v[78:81]
	v_mfma_f32_16x16x32_bf16 v[78:81], v[130:133], v[214:217], v[78:81]
	v_mfma_f32_16x16x32_bf16 v[70:73], v[160:163], v[214:217], v[70:73]
	v_mfma_f32_16x16x32_bf16 v[70:73], v[164:167], v[218:221], v[70:73]
	v_mfma_f32_16x16x32_bf16 v[66:69], v[186:189], v[218:221], v[66:69]
	v_mfma_f32_16x16x32_bf16 v[66:69], v[168:171], v[214:217], v[66:69]
	v_mfma_f32_16x16x32_bf16 v[82:85], v[168:171], v[206:209], v[82:85]
	v_mfma_f32_16x16x32_bf16 v[82:85], v[186:189], v[210:213], v[82:85]
	v_mfma_f32_16x16x32_bf16 v[86:89], v[164:167], v[210:213], v[86:89]
	v_mfma_f32_16x16x32_bf16 v[86:89], v[160:163], v[206:209], v[86:89]
	v_mfma_f32_16x16x32_bf16 v[102:105], v[160:163], v[198:201], v[102:105]
	v_mfma_f32_16x16x32_bf16 v[102:105], v[164:167], v[202:205], v[102:105]
	v_mfma_f32_16x16x32_bf16 v[98:101], v[186:189], v[202:205], v[98:101]
	v_mfma_f32_16x16x32_bf16 v[98:101], v[168:171], v[198:201], v[98:101]
	v_mfma_f32_16x16x32_bf16 v[114:117], v[168:171], v[190:193], v[114:117]
	v_mfma_f32_16x16x32_bf16 v[114:117], v[186:189], v[194:197], v[114:117]
	v_mfma_f32_16x16x32_bf16 v[118:121], v[164:167], v[194:197], v[118:121]
	v_mfma_f32_16x16x32_bf16 v[118:121], v[160:163], v[190:193], v[118:121]
	s_barrier
	s_add_i32 s30, s62, s49
	v_lshl_add_u64 v[172:173], v[172:173], 0, s[98:99]
	s_mov_b32 m0, s30
	ds_read_b128 v[190:193], v184 offset:49152
	ds_read_b128 v[194:197], v184 offset:50176
	ds_read_b128 v[198:201], v184 offset:51200
	ds_read_b128 v[202:205], v184 offset:52224
	ds_read_b128 v[206:209], v184 offset:53248
	ds_read_b128 v[210:213], v184 offset:54272
	ds_read_b128 v[214:217], v184 offset:55296
	ds_read_b128 v[218:221], v184 offset:56320
	global_load_lds_dwordx4 v[172:173], off
	v_lshl_add_u64 v[172:173], v[222:223], 0, s[98:99]
	s_add_i32 m0, s30, 0x2000
	s_add_i32 s30, s63, s49
	global_load_lds_dwordx4 v[172:173], off
	v_lshl_add_u64 v[172:173], v[236:237], 0, s[98:99]
	s_mov_b32 m0, s30
	s_nop 0
	global_load_lds_dwordx4 v[172:173], off
	v_lshl_add_u64 v[172:173], v[238:239], 0, s[98:99]
	s_add_i32 m0, s30, 0x2000
	s_nop 0
	global_load_lds_dwordx4 v[172:173], off
	s_mov_b32 m0, s95
	s_nop 0
	global_load_lds_dwordx4 v138, s[64:65]
	s_mov_b32 m0, s54
	s_nop 0
	global_load_lds_dwordx4 v140, s[64:65]
	s_waitcnt vmcnt(8)
	s_waitcnt lgkmcnt(0)
	s_barrier
	s_waitcnt lgkmcnt(0)
	v_mfma_f32_16x16x32_bf16 v[62:65], v[130:133], v[190:193], v[62:65]
	v_mfma_f32_16x16x32_bf16 v[62:65], v[134:137], v[194:197], v[62:65]
	v_mfma_f32_16x16x32_bf16 v[58:61], v[156:159], v[194:197], v[58:61]
	v_mfma_f32_16x16x32_bf16 v[58:61], v[152:155], v[190:193], v[58:61]
	v_mfma_f32_16x16x32_bf16 v[42:45], v[152:155], v[198:201], v[42:45]
	v_mfma_f32_16x16x32_bf16 v[42:45], v[156:159], v[202:205], v[42:45]
	v_mfma_f32_16x16x32_bf16 v[46:49], v[134:137], v[202:205], v[46:49]
	v_mfma_f32_16x16x32_bf16 v[46:49], v[130:133], v[198:201], v[46:49]
	v_mfma_f32_16x16x32_bf16 v[30:33], v[130:133], v[206:209], v[30:33]
	v_mfma_f32_16x16x32_bf16 v[30:33], v[134:137], v[210:213], v[30:33]
	v_mfma_f32_16x16x32_bf16 v[26:29], v[156:159], v[210:213], v[26:29]
	v_mfma_f32_16x16x32_bf16 v[26:29], v[152:155], v[206:209], v[26:29]
	v_mfma_f32_16x16x32_bf16 v[10:13], v[152:155], v[214:217], v[10:13]
	v_mfma_f32_16x16x32_bf16 v[10:13], v[156:159], v[218:221], v[10:13]
	v_mfma_f32_16x16x32_bf16 v[14:17], v[134:137], v[218:221], v[14:17]
	v_mfma_f32_16x16x32_bf16 v[14:17], v[130:133], v[214:217], v[14:17]
	v_mfma_f32_16x16x32_bf16 v[6:9], v[160:163], v[214:217], v[6:9]
	v_mfma_f32_16x16x32_bf16 v[6:9], v[164:167], v[218:221], v[6:9]
	v_mfma_f32_16x16x32_bf16 v[2:5], v[186:189], v[218:221], v[2:5]
	v_mfma_f32_16x16x32_bf16 v[2:5], v[168:171], v[214:217], v[2:5]
	v_mfma_f32_16x16x32_bf16 v[18:21], v[168:171], v[206:209], v[18:21]
	v_mfma_f32_16x16x32_bf16 v[18:21], v[186:189], v[210:213], v[18:21]
	v_mfma_f32_16x16x32_bf16 v[22:25], v[164:167], v[210:213], v[22:25]
	v_mfma_f32_16x16x32_bf16 v[22:25], v[160:163], v[206:209], v[22:25]
	v_mfma_f32_16x16x32_bf16 v[38:41], v[160:163], v[198:201], v[38:41]
	v_mfma_f32_16x16x32_bf16 v[38:41], v[164:167], v[202:205], v[38:41]
	v_mfma_f32_16x16x32_bf16 v[34:37], v[186:189], v[202:205], v[34:37]
	v_mfma_f32_16x16x32_bf16 v[34:37], v[168:171], v[198:201], v[34:37]
	v_mfma_f32_16x16x32_bf16 v[50:53], v[168:171], v[190:193], v[50:53]
	v_mfma_f32_16x16x32_bf16 v[50:53], v[186:189], v[194:197], v[50:53]
	v_mfma_f32_16x16x32_bf16 v[54:57], v[164:167], v[194:197], v[54:57]
	v_mfma_f32_16x16x32_bf16 v[54:57], v[160:163], v[190:193], v[54:57]
	s_barrier
	s_add_u32 s28, s28, 0x100
	s_addc_u32 s29, s29, 0
	s_add_u32 s23, s23, 0x100
	s_addc_u32 s40, s40, 0
	s_cmp_ge_i32 s41, s61
	s_mov_b32 s30, s41
	s_cbranch_scc1 .Lpeel_done_217
.LBB0_217:
	s_add_i32 s41, s30, 2
	s_add_u32 vcc_lo, s28, 0x80
	s_addc_u32 s31, s29, 0
	s_add_i32 s62, 0, 0x10000
	s_cmp_eq_u32 s13, s30
	s_cselect_b32 s31, s25, s31
	s_cselect_b32 s30, s24, vcc_lo
	v_add_u32_e32 v145, s62, v175
	s_cselect_b32 vcc_hi, s27, s40
	s_cselect_b32 vcc_lo, s26, s23
	s_add_i32 s63, 0, 0x14000
	ds_read_b128 v[130:133], v145
	ds_read_b128 v[134:137], v145 offset:1024
	ds_read_b128 v[152:155], v145 offset:2048
	ds_read_b128 v[156:159], v145 offset:3072
	v_add_u32_e32 v145, s63, v175
	ds_read_b128 v[160:163], v145
	ds_read_b128 v[164:167], v145 offset:1024
	ds_read_b128 v[168:171], v145 offset:2048
	ds_read_b128 v[186:189], v145 offset:3072
	v_lshl_add_u64 v[172:173], s[28:29], 0, v[148:149]
	s_add_i32 m0, s93, 0xc000
	ds_read_b128 v[190:193], v184
	ds_read_b128 v[194:197], v184 offset:1024
	ds_read_b128 v[198:201], v184 offset:2048
	ds_read_b128 v[202:205], v184 offset:3072
	ds_read_b128 v[206:209], v184 offset:4096
	ds_read_b128 v[210:213], v184 offset:5120
	ds_read_b128 v[214:217], v184 offset:6144
	ds_read_b128 v[218:221], v184 offset:7168
	global_load_lds_dwordx4 v[172:173], off
	v_lshl_add_u64 v[172:173], s[28:29], 0, v[150:151]
	s_add_i32 m0, s93, 0xe000
	s_nop 0
	global_load_lds_dwordx4 v[172:173], off
	s_waitcnt vmcnt(8)
	s_waitcnt lgkmcnt(0)
	s_barrier
	s_waitcnt lgkmcnt(0)
	v_mfma_f32_16x16x32_bf16 v[126:129], v[130:133], v[190:193], v[126:129]
	v_mfma_f32_16x16x32_bf16 v[126:129], v[134:137], v[194:197], v[126:129]
	v_mfma_f32_16x16x32_bf16 v[122:125], v[156:159], v[194:197], v[122:125]
	v_mfma_f32_16x16x32_bf16 v[122:125], v[152:155], v[190:193], v[122:125]
	v_mfma_f32_16x16x32_bf16 v[106:109], v[152:155], v[198:201], v[106:109]
	v_mfma_f32_16x16x32_bf16 v[106:109], v[156:159], v[202:205], v[106:109]
	v_mfma_f32_16x16x32_bf16 v[110:113], v[134:137], v[202:205], v[110:113]
	v_mfma_f32_16x16x32_bf16 v[110:113], v[130:133], v[198:201], v[110:113]
	v_mfma_f32_16x16x32_bf16 v[94:97], v[130:133], v[206:209], v[94:97]
	v_mfma_f32_16x16x32_bf16 v[94:97], v[134:137], v[210:213], v[94:97]
	v_mfma_f32_16x16x32_bf16 v[90:93], v[156:159], v[210:213], v[90:93]
	v_mfma_f32_16x16x32_bf16 v[90:93], v[152:155], v[206:209], v[90:93]
	v_mfma_f32_16x16x32_bf16 v[74:77], v[152:155], v[214:217], v[74:77]
	v_mfma_f32_16x16x32_bf16 v[74:77], v[156:159], v[218:221], v[74:77]
	v_mfma_f32_16x16x32_bf16 v[78:81], v[134:137], v[218:221], v[78:81]
	v_mfma_f32_16x16x32_bf16 v[78:81], v[130:133], v[214:217], v[78:81]
	v_mfma_f32_16x16x32_bf16 v[70:73], v[160:163], v[214:217], v[70:73]
	v_mfma_f32_16x16x32_bf16 v[70:73], v[164:167], v[218:221], v[70:73]
	v_mfma_f32_16x16x32_bf16 v[66:69], v[186:189], v[218:221], v[66:69]
	v_mfma_f32_16x16x32_bf16 v[66:69], v[168:171], v[214:217], v[66:69]
	v_mfma_f32_16x16x32_bf16 v[82:85], v[168:171], v[206:209], v[82:85]
	v_mfma_f32_16x16x32_bf16 v[82:85], v[186:189], v[210:213], v[82:85]
	v_mfma_f32_16x16x32_bf16 v[86:89], v[164:167], v[210:213], v[86:89]
	v_mfma_f32_16x16x32_bf16 v[86:89], v[160:163], v[206:209], v[86:89]
	v_mfma_f32_16x16x32_bf16 v[102:105], v[160:163], v[198:201], v[102:105]
	v_mfma_f32_16x16x32_bf16 v[102:105], v[164:167], v[202:205], v[102:105]
	v_mfma_f32_16x16x32_bf16 v[98:101], v[186:189], v[202:205], v[98:101]
	v_mfma_f32_16x16x32_bf16 v[98:101], v[168:171], v[198:201], v[98:101]
	v_mfma_f32_16x16x32_bf16 v[114:117], v[168:171], v[190:193], v[114:117]
	v_mfma_f32_16x16x32_bf16 v[114:117], v[186:189], v[194:197], v[114:117]
	v_mfma_f32_16x16x32_bf16 v[118:121], v[164:167], v[194:197], v[118:121]
	v_mfma_f32_16x16x32_bf16 v[118:121], v[160:163], v[190:193], v[118:121]
	s_barrier
	s_add_i32 s62, s62, s49
	v_lshl_add_u64 v[172:173], vcc, 0, v[0:1]
	s_mov_b32 m0, s62
	ds_read_b128 v[190:193], v184 offset:16384
	ds_read_b128 v[194:197], v184 offset:17408
	ds_read_b128 v[198:201], v184 offset:18432
	ds_read_b128 v[202:205], v184 offset:19456
	ds_read_b128 v[206:209], v184 offset:20480
	ds_read_b128 v[210:213], v184 offset:21504
	ds_read_b128 v[214:217], v184 offset:22528
	ds_read_b128 v[218:221], v184 offset:23552
	global_load_lds_dwordx4 v[172:173], off
	s_add_i32 m0, s62, 0x2000
	v_lshl_add_u64 v[222:223], vcc, 0, v[142:143]
	s_add_u32 vcc_lo, vcc_lo, s96
	s_addc_u32 vcc_hi, vcc_hi, 0
	s_add_i32 s62, s63, s49
	global_load_lds_dwordx4 v[222:223], off
	v_lshl_add_u64 v[236:237], vcc, 0, v[0:1]
	s_mov_b32 m0, s62
	v_lshl_add_u64 v[238:239], vcc, 0, v[142:143]
	global_load_lds_dwordx4 v[236:237], off
	s_add_i32 m0, s62, 0x2000
	s_add_u32 s64, s30, s98
	s_addc_u32 s65, s31, s99
	global_load_lds_dwordx4 v[238:239], off
	s_mov_b32 m0, s93
	global_load_lds_dwordx4 v138, s[30:31]
	s_mov_b32 m0, s88
	s_nop 0
	global_load_lds_dwordx4 v140, s[30:31]
	s_waitcnt vmcnt(8)
	s_waitcnt lgkmcnt(0)
	s_barrier
	s_waitcnt lgkmcnt(0)
	v_mfma_f32_16x16x32_bf16 v[62:65], v[130:133], v[190:193], v[62:65]
	v_mfma_f32_16x16x32_bf16 v[62:65], v[134:137], v[194:197], v[62:65]
	v_mfma_f32_16x16x32_bf16 v[58:61], v[156:159], v[194:197], v[58:61]
	v_mfma_f32_16x16x32_bf16 v[58:61], v[152:155], v[190:193], v[58:61]
	v_mfma_f32_16x16x32_bf16 v[42:45], v[152:155], v[198:201], v[42:45]
	v_mfma_f32_16x16x32_bf16 v[42:45], v[156:159], v[202:205], v[42:45]
	v_mfma_f32_16x16x32_bf16 v[46:49], v[134:137], v[202:205], v[46:49]
	v_mfma_f32_16x16x32_bf16 v[46:49], v[130:133], v[198:201], v[46:49]
	v_mfma_f32_16x16x32_bf16 v[30:33], v[130:133], v[206:209], v[30:33]
	v_mfma_f32_16x16x32_bf16 v[30:33], v[134:137], v[210:213], v[30:33]
	v_mfma_f32_16x16x32_bf16 v[26:29], v[156:159], v[210:213], v[26:29]
	v_mfma_f32_16x16x32_bf16 v[26:29], v[152:155], v[206:209], v[26:29]
	v_mfma_f32_16x16x32_bf16 v[10:13], v[152:155], v[214:217], v[10:13]
	v_mfma_f32_16x16x32_bf16 v[10:13], v[156:159], v[218:221], v[10:13]
	v_mfma_f32_16x16x32_bf16 v[14:17], v[134:137], v[218:221], v[14:17]
	v_mfma_f32_16x16x32_bf16 v[14:17], v[130:133], v[214:217], v[14:17]
	v_mfma_f32_16x16x32_bf16 v[6:9], v[160:163], v[214:217], v[6:9]
	v_mfma_f32_16x16x32_bf16 v[6:9], v[164:167], v[218:221], v[6:9]
	v_mfma_f32_16x16x32_bf16 v[2:5], v[186:189], v[218:221], v[2:5]
	v_mfma_f32_16x16x32_bf16 v[2:5], v[168:171], v[214:217], v[2:5]
	v_mfma_f32_16x16x32_bf16 v[18:21], v[168:171], v[206:209], v[18:21]
	v_mfma_f32_16x16x32_bf16 v[18:21], v[186:189], v[210:213], v[18:21]
	v_mfma_f32_16x16x32_bf16 v[22:25], v[164:167], v[210:213], v[22:25]
	v_mfma_f32_16x16x32_bf16 v[22:25], v[160:163], v[206:209], v[22:25]
	v_mfma_f32_16x16x32_bf16 v[38:41], v[160:163], v[198:201], v[38:41]
	v_mfma_f32_16x16x32_bf16 v[38:41], v[164:167], v[202:205], v[38:41]
	v_mfma_f32_16x16x32_bf16 v[34:37], v[186:189], v[202:205], v[34:37]
	v_mfma_f32_16x16x32_bf16 v[34:37], v[168:171], v[198:201], v[34:37]
	v_mfma_f32_16x16x32_bf16 v[50:53], v[168:171], v[190:193], v[50:53]
	v_mfma_f32_16x16x32_bf16 v[50:53], v[186:189], v[194:197], v[50:53]
	v_mfma_f32_16x16x32_bf16 v[54:57], v[164:167], v[194:197], v[54:57]
	v_mfma_f32_16x16x32_bf16 v[54:57], v[160:163], v[190:193], v[54:57]
	s_barrier
	s_add_i32 s62, 0, 0x18000
	v_add_u32_e32 v145, s62, v175
	s_add_i32 s63, 0, 0x1c000
	ds_read_b128 v[130:133], v145
	ds_read_b128 v[134:137], v145 offset:1024
	ds_read_b128 v[152:155], v145 offset:2048
	ds_read_b128 v[156:159], v145 offset:3072
	v_add_u32_e32 v145, s63, v175
	ds_read_b128 v[160:163], v145
	ds_read_b128 v[164:167], v145 offset:1024
	ds_read_b128 v[168:171], v145 offset:2048
	ds_read_b128 v[186:189], v145 offset:3072
	s_add_u32 s30, s30, s96
	s_addc_u32 s31, s31, 0
	s_mov_b32 m0, s89
	ds_read_b128 v[190:193], v184 offset:32768
	ds_read_b128 v[194:197], v184 offset:33792
	ds_read_b128 v[198:201], v184 offset:34816
	ds_read_b128 v[202:205], v184 offset:35840
	ds_read_b128 v[206:209], v184 offset:36864
	ds_read_b128 v[210:213], v184 offset:37888
	ds_read_b128 v[214:217], v184 offset:38912
	ds_read_b128 v[218:221], v184 offset:39936
	global_load_lds_dwordx4 v138, s[30:31]
	s_mov_b32 m0, s52
	s_nop 0
	global_load_lds_dwordx4 v140, s[30:31]
	s_waitcnt vmcnt(8)
	s_waitcnt lgkmcnt(0)
	s_barrier
	s_waitcnt lgkmcnt(0)
	v_mfma_f32_16x16x32_bf16 v[126:129], v[130:133], v[190:193], v[126:129]
	v_mfma_f32_16x16x32_bf16 v[126:129], v[134:137], v[194:197], v[126:129]
	v_mfma_f32_16x16x32_bf16 v[122:125], v[156:159], v[194:197], v[122:125]
	v_mfma_f32_16x16x32_bf16 v[122:125], v[152:155], v[190:193], v[122:125]
	v_mfma_f32_16x16x32_bf16 v[106:109], v[152:155], v[198:201], v[106:109]
	v_mfma_f32_16x16x32_bf16 v[106:109], v[156:159], v[202:205], v[106:109]
	v_mfma_f32_16x16x32_bf16 v[110:113], v[134:137], v[202:205], v[110:113]
	v_mfma_f32_16x16x32_bf16 v[110:113], v[130:133], v[198:201], v[110:113]
	v_mfma_f32_16x16x32_bf16 v[94:97], v[130:133], v[206:209], v[94:97]
	v_mfma_f32_16x16x32_bf16 v[94:97], v[134:137], v[210:213], v[94:97]
	v_mfma_f32_16x16x32_bf16 v[90:93], v[156:159], v[210:213], v[90:93]
	v_mfma_f32_16x16x32_bf16 v[90:93], v[152:155], v[206:209], v[90:93]
	v_mfma_f32_16x16x32_bf16 v[74:77], v[152:155], v[214:217], v[74:77]
	v_mfma_f32_16x16x32_bf16 v[74:77], v[156:159], v[218:221], v[74:77]
	v_mfma_f32_16x16x32_bf16 v[78:81], v[134:137], v[218:221], v[78:81]
	v_mfma_f32_16x16x32_bf16 v[78:81], v[130:133], v[214:217], v[78:81]
	v_mfma_f32_16x16x32_bf16 v[70:73], v[160:163], v[214:217], v[70:73]
	v_mfma_f32_16x16x32_bf16 v[70:73], v[164:167], v[218:221], v[70:73]
	v_mfma_f32_16x16x32_bf16 v[66:69], v[186:189], v[218:221], v[66:69]
	v_mfma_f32_16x16x32_bf16 v[66:69], v[168:171], v[214:217], v[66:69]
	v_mfma_f32_16x16x32_bf16 v[82:85], v[168:171], v[206:209], v[82:85]
	v_mfma_f32_16x16x32_bf16 v[82:85], v[186:189], v[210:213], v[82:85]
	v_mfma_f32_16x16x32_bf16 v[86:89], v[164:167], v[210:213], v[86:89]
	v_mfma_f32_16x16x32_bf16 v[86:89], v[160:163], v[206:209], v[86:89]
	v_mfma_f32_16x16x32_bf16 v[102:105], v[160:163], v[198:201], v[102:105]
	v_mfma_f32_16x16x32_bf16 v[102:105], v[164:167], v[202:205], v[102:105]
	v_mfma_f32_16x16x32_bf16 v[98:101], v[186:189], v[202:205], v[98:101]
	v_mfma_f32_16x16x32_bf16 v[98:101], v[168:171], v[198:201], v[98:101]
	v_mfma_f32_16x16x32_bf16 v[114:117], v[168:171], v[190:193], v[114:117]
	v_mfma_f32_16x16x32_bf16 v[114:117], v[186:189], v[194:197], v[114:117]
	v_mfma_f32_16x16x32_bf16 v[118:121], v[164:167], v[194:197], v[118:121]
	v_mfma_f32_16x16x32_bf16 v[118:121], v[160:163], v[190:193], v[118:121]
	s_barrier
	s_add_i32 s30, s62, s49
	v_lshl_add_u64 v[172:173], v[172:173], 0, s[98:99]
	s_mov_b32 m0, s30
	ds_read_b128 v[190:193], v184 offset:49152
	ds_read_b128 v[194:197], v184 offset:50176
	ds_read_b128 v[198:201], v184 offset:51200
	ds_read_b128 v[202:205], v184 offset:52224
	ds_read_b128 v[206:209], v184 offset:53248
	ds_read_b128 v[210:213], v184 offset:54272
	ds_read_b128 v[214:217], v184 offset:55296
	ds_read_b128 v[218:221], v184 offset:56320
	global_load_lds_dwordx4 v[172:173], off
	v_lshl_add_u64 v[172:173], v[222:223], 0, s[98:99]
	s_add_i32 m0, s30, 0x2000
	s_add_i32 s30, s63, s49
	global_load_lds_dwordx4 v[172:173], off
	v_lshl_add_u64 v[172:173], v[236:237], 0, s[98:99]
	s_mov_b32 m0, s30
	s_nop 0
	global_load_lds_dwordx4 v[172:173], off
	v_lshl_add_u64 v[172:173], v[238:239], 0, s[98:99]
	s_add_i32 m0, s30, 0x2000
	s_nop 0
	global_load_lds_dwordx4 v[172:173], off
	s_mov_b32 m0, s95
	s_nop 0
	global_load_lds_dwordx4 v138, s[64:65]
	s_mov_b32 m0, s54
	s_nop 0
	global_load_lds_dwordx4 v140, s[64:65]
	s_waitcnt vmcnt(8)
	s_waitcnt lgkmcnt(0)
	s_barrier
	s_waitcnt lgkmcnt(0)
	v_mfma_f32_16x16x32_bf16 v[62:65], v[130:133], v[190:193], v[62:65]
	v_mfma_f32_16x16x32_bf16 v[62:65], v[134:137], v[194:197], v[62:65]
	v_mfma_f32_16x16x32_bf16 v[58:61], v[156:159], v[194:197], v[58:61]
	v_mfma_f32_16x16x32_bf16 v[58:61], v[152:155], v[190:193], v[58:61]
	v_mfma_f32_16x16x32_bf16 v[42:45], v[152:155], v[198:201], v[42:45]
	v_mfma_f32_16x16x32_bf16 v[42:45], v[156:159], v[202:205], v[42:45]
	v_mfma_f32_16x16x32_bf16 v[46:49], v[134:137], v[202:205], v[46:49]
	v_mfma_f32_16x16x32_bf16 v[46:49], v[130:133], v[198:201], v[46:49]
	v_mfma_f32_16x16x32_bf16 v[30:33], v[130:133], v[206:209], v[30:33]
	v_mfma_f32_16x16x32_bf16 v[30:33], v[134:137], v[210:213], v[30:33]
	v_mfma_f32_16x16x32_bf16 v[26:29], v[156:159], v[210:213], v[26:29]
	v_mfma_f32_16x16x32_bf16 v[26:29], v[152:155], v[206:209], v[26:29]
	v_mfma_f32_16x16x32_bf16 v[10:13], v[152:155], v[214:217], v[10:13]
	v_mfma_f32_16x16x32_bf16 v[10:13], v[156:159], v[218:221], v[10:13]
	v_mfma_f32_16x16x32_bf16 v[14:17], v[134:137], v[218:221], v[14:17]
	v_mfma_f32_16x16x32_bf16 v[14:17], v[130:133], v[214:217], v[14:17]
	v_mfma_f32_16x16x32_bf16 v[6:9], v[160:163], v[214:217], v[6:9]
	v_mfma_f32_16x16x32_bf16 v[6:9], v[164:167], v[218:221], v[6:9]
	v_mfma_f32_16x16x32_bf16 v[2:5], v[186:189], v[218:221], v[2:5]
	v_mfma_f32_16x16x32_bf16 v[2:5], v[168:171], v[214:217], v[2:5]
	v_mfma_f32_16x16x32_bf16 v[18:21], v[168:171], v[206:209], v[18:21]
	v_mfma_f32_16x16x32_bf16 v[18:21], v[186:189], v[210:213], v[18:21]
	v_mfma_f32_16x16x32_bf16 v[22:25], v[164:167], v[210:213], v[22:25]
	v_mfma_f32_16x16x32_bf16 v[22:25], v[160:163], v[206:209], v[22:25]
	v_mfma_f32_16x16x32_bf16 v[38:41], v[160:163], v[198:201], v[38:41]
	v_mfma_f32_16x16x32_bf16 v[38:41], v[164:167], v[202:205], v[38:41]
	v_mfma_f32_16x16x32_bf16 v[34:37], v[186:189], v[202:205], v[34:37]
	v_mfma_f32_16x16x32_bf16 v[34:37], v[168:171], v[198:201], v[34:37]
	v_mfma_f32_16x16x32_bf16 v[50:53], v[168:171], v[190:193], v[50:53]
	v_mfma_f32_16x16x32_bf16 v[50:53], v[186:189], v[194:197], v[50:53]
	v_mfma_f32_16x16x32_bf16 v[54:57], v[164:167], v[194:197], v[54:57]
	v_mfma_f32_16x16x32_bf16 v[54:57], v[160:163], v[190:193], v[54:57]
	s_barrier
	s_add_u32 s28, s28, 0x100
	s_addc_u32 s29, s29, 0
	s_add_u32 s23, s23, 0x100
	s_addc_u32 s40, s40, 0
	s_cmp_ge_i32 s41, s61
	s_mov_b32 s30, s41
	s_cbranch_scc0 .LBB0_217

.LBB0_373:
	s_ashr_i32 s17, s16, 31
	s_lshl_b64 s[20:21], s[16:17], 19
	s_add_u32 s20, s37, s20
	s_addc_u32 s21, s40, s21
	s_and_b64 s[22:23], s[18:19], exec
	s_cselect_b32 s17, s21, s29
	s_cselect_b32 s25, s20, s28
	s_ashr_i32 s15, s14, 31
	s_lshl_b64 s[22:23], s[14:15], 19
	s_add_u32 s22, s41, s22
	s_addc_u32 s23, s42, s23
	s_and_b64 s[38:39], s[18:19], exec
	s_cselect_b32 s15, s23, s31
	s_cselect_b32 s53, s22, s30
	s_add_u32 s28, s28, 0x40080
	s_addc_u32 s29, s29, 0
	s_add_u32 s54, s30, 0x100
	s_addc_u32 s55, s31, 0
	s_mov_b32 s56, -2
	s_add_u32 s30, s28, 0xfffc0080
	s_addc_u32 s31, s29, -1
	s_add_i32 s57, 0, 0x10000
	s_cmp_eq_u32 s56, 12
	s_cselect_b32 s39, s17, s31
	s_cselect_b32 s38, s25, s30
	s_cselect_b32 s31, s15, s55
	s_cselect_b32 s30, s53, s54
	s_add_i32 s60, 0, 0x14000
	v_add_u32_e32 v156, s57, v145
	v_add_u32_e32 v172, s60, v145
	ds_read_b128 v[140:143], v156
	ds_read_b128 v[148:151], v156 offset:1024
	ds_read_b128 v[152:155], v156 offset:2048
	ds_read_b128 v[156:159], v156 offset:3072
	ds_read_b128 v[160:163], v172
	ds_read_b128 v[164:167], v172 offset:1024
	ds_read_b128 v[168:171], v172 offset:2048
	ds_read_b128 v[172:175], v172 offset:3072
	s_add_i32 m0, s27, 0xc000
	ds_read_b128 v[176:179], v147
	ds_read_b128 v[180:183], v147 offset:1024
	ds_read_b128 v[184:187], v147 offset:2048
	ds_read_b128 v[188:191], v147 offset:3072
	ds_read_b128 v[192:195], v147 offset:4096
	ds_read_b128 v[196:199], v147 offset:5120
	ds_read_b128 v[200:203], v147 offset:6144
	ds_read_b128 v[204:207], v147 offset:7168
	global_load_lds_dwordx4 v136, s[28:29]
	s_add_i32 m0, s27, 0xe000
	s_nop 0
	global_load_lds_dwordx4 v138, s[28:29]
	s_waitcnt vmcnt(8)
	s_waitcnt lgkmcnt(0)
	s_barrier
	s_waitcnt lgkmcnt(0)
	v_mfma_f32_16x16x32_bf16 v[122:125], v[140:143], v[176:179], 0
	v_mfma_f32_16x16x32_bf16 v[122:125], v[148:151], v[180:183], v[122:125]
	v_mfma_f32_16x16x32_bf16 v[114:117], v[156:159], v[180:183], 0
	v_mfma_f32_16x16x32_bf16 v[114:117], v[152:155], v[176:179], v[114:117]
	v_mfma_f32_16x16x32_bf16 v[98:101], v[152:155], v[184:187], 0
	v_mfma_f32_16x16x32_bf16 v[98:101], v[156:159], v[188:191], v[98:101]
	v_mfma_f32_16x16x32_bf16 v[106:109], v[148:151], v[188:191], 0
	v_mfma_f32_16x16x32_bf16 v[106:109], v[140:143], v[184:187], v[106:109]
	v_mfma_f32_16x16x32_bf16 v[90:93], v[140:143], v[192:195], 0
	v_mfma_f32_16x16x32_bf16 v[90:93], v[148:151], v[196:199], v[90:93]
	v_mfma_f32_16x16x32_bf16 v[82:85], v[156:159], v[196:199], 0
	v_mfma_f32_16x16x32_bf16 v[82:85], v[152:155], v[192:195], v[82:85]
	v_mfma_f32_16x16x32_bf16 v[66:69], v[152:155], v[200:203], 0
	v_mfma_f32_16x16x32_bf16 v[66:69], v[156:159], v[204:207], v[66:69]
	v_mfma_f32_16x16x32_bf16 v[74:77], v[148:151], v[204:207], 0
	v_mfma_f32_16x16x32_bf16 v[74:77], v[140:143], v[200:203], v[74:77]
	v_mfma_f32_16x16x32_bf16 v[78:81], v[160:163], v[200:203], 0
	v_mfma_f32_16x16x32_bf16 v[78:81], v[164:167], v[204:207], v[78:81]
	v_mfma_f32_16x16x32_bf16 v[70:73], v[172:175], v[204:207], 0
	v_mfma_f32_16x16x32_bf16 v[70:73], v[168:171], v[200:203], v[70:73]
	v_mfma_f32_16x16x32_bf16 v[86:89], v[168:171], v[192:195], 0
	v_mfma_f32_16x16x32_bf16 v[86:89], v[172:175], v[196:199], v[86:89]
	v_mfma_f32_16x16x32_bf16 v[94:97], v[164:167], v[196:199], 0
	v_mfma_f32_16x16x32_bf16 v[94:97], v[160:163], v[192:195], v[94:97]
	v_mfma_f32_16x16x32_bf16 v[110:113], v[160:163], v[184:187], 0
	v_mfma_f32_16x16x32_bf16 v[110:113], v[164:167], v[188:191], v[110:113]
	v_mfma_f32_16x16x32_bf16 v[102:105], v[172:175], v[188:191], 0
	v_mfma_f32_16x16x32_bf16 v[102:105], v[168:171], v[184:187], v[102:105]
	v_mfma_f32_16x16x32_bf16 v[118:121], v[168:171], v[176:179], 0
	v_mfma_f32_16x16x32_bf16 v[118:121], v[172:175], v[180:183], v[118:121]
	v_mfma_f32_16x16x32_bf16 v[126:129], v[164:167], v[180:183], 0
	v_mfma_f32_16x16x32_bf16 v[126:129], v[160:163], v[176:179], v[126:129]
	s_barrier
	s_add_i32 s57, s57, s43
	s_add_u32 s64, s30, s98
	s_addc_u32 s65, s31, s99
	s_mov_b32 m0, s57
	ds_read_b128 v[176:179], v147 offset:16384
	ds_read_b128 v[180:183], v147 offset:17408
	ds_read_b128 v[184:187], v147 offset:18432
	ds_read_b128 v[188:191], v147 offset:19456
	ds_read_b128 v[192:195], v147 offset:20480
	ds_read_b128 v[196:199], v147 offset:21504
	ds_read_b128 v[200:203], v147 offset:22528
	ds_read_b128 v[204:207], v147 offset:23552
	global_load_lds_dwordx4 v0, s[30:31]
	s_add_i32 m0, s57, 0x2000
	s_add_u32 s58, s30, 0x40000
	s_addc_u32 s59, s31, 0
	s_add_i32 s57, s60, s43
	global_load_lds_dwordx4 v134, s[30:31]
	s_mov_b32 m0, s57
	global_load_lds_dwordx4 v0, s[58:59]
	s_add_i32 m0, s57, 0x2000
	s_nop 0
	global_load_lds_dwordx4 v134, s[58:59]
	s_add_u32 s66, s38, s98
	s_addc_u32 s67, s39, s99
	s_mov_b32 m0, s27
	s_nop 0
	global_load_lds_dwordx4 v130, s[38:39]
	s_mov_b32 m0, s44
	s_nop 0
	global_load_lds_dwordx4 v132, s[38:39]
	s_waitcnt vmcnt(8)
	s_waitcnt lgkmcnt(0)
	s_barrier
	s_waitcnt lgkmcnt(0)
	v_mfma_f32_16x16x32_bf16 v[58:61], v[140:143], v[176:179], 0
	v_mfma_f32_16x16x32_bf16 v[58:61], v[148:151], v[180:183], v[58:61]
	v_mfma_f32_16x16x32_bf16 v[50:53], v[156:159], v[180:183], 0
	v_mfma_f32_16x16x32_bf16 v[50:53], v[152:155], v[176:179], v[50:53]
	v_mfma_f32_16x16x32_bf16 v[34:37], v[152:155], v[184:187], 0
	v_mfma_f32_16x16x32_bf16 v[34:37], v[156:159], v[188:191], v[34:37]
	v_mfma_f32_16x16x32_bf16 v[42:45], v[148:151], v[188:191], 0
	v_mfma_f32_16x16x32_bf16 v[42:45], v[140:143], v[184:187], v[42:45]
	v_mfma_f32_16x16x32_bf16 v[26:29], v[140:143], v[192:195], 0
	v_mfma_f32_16x16x32_bf16 v[26:29], v[148:151], v[196:199], v[26:29]
	v_mfma_f32_16x16x32_bf16 v[18:21], v[156:159], v[196:199], 0
	v_mfma_f32_16x16x32_bf16 v[18:21], v[152:155], v[192:195], v[18:21]
	v_mfma_f32_16x16x32_bf16 v[6:9], v[152:155], v[200:203], 0
	v_mfma_f32_16x16x32_bf16 v[6:9], v[156:159], v[204:207], v[6:9]
	v_mfma_f32_16x16x32_bf16 v[10:13], v[148:151], v[204:207], 0
	v_mfma_f32_16x16x32_bf16 v[10:13], v[140:143], v[200:203], v[10:13]
	v_mfma_f32_16x16x32_bf16 v[14:17], v[160:163], v[200:203], 0
	v_mfma_f32_16x16x32_bf16 v[14:17], v[164:167], v[204:207], v[14:17]
	v_mfma_f32_16x16x32_bf16 v[2:5], v[172:175], v[204:207], 0
	v_mfma_f32_16x16x32_bf16 v[2:5], v[168:171], v[200:203], v[2:5]
	v_mfma_f32_16x16x32_bf16 v[22:25], v[168:171], v[192:195], 0
	v_mfma_f32_16x16x32_bf16 v[22:25], v[172:175], v[196:199], v[22:25]
	v_mfma_f32_16x16x32_bf16 v[30:33], v[164:167], v[196:199], 0
	v_mfma_f32_16x16x32_bf16 v[30:33], v[160:163], v[192:195], v[30:33]
	v_mfma_f32_16x16x32_bf16 v[46:49], v[160:163], v[184:187], 0
	v_mfma_f32_16x16x32_bf16 v[46:49], v[164:167], v[188:191], v[46:49]
	v_mfma_f32_16x16x32_bf16 v[38:41], v[172:175], v[188:191], 0
	v_mfma_f32_16x16x32_bf16 v[38:41], v[168:171], v[184:187], v[38:41]
	v_mfma_f32_16x16x32_bf16 v[54:57], v[168:171], v[176:179], 0
	v_mfma_f32_16x16x32_bf16 v[54:57], v[172:175], v[180:183], v[54:57]
	v_mfma_f32_16x16x32_bf16 v[62:65], v[164:167], v[180:183], 0
	v_mfma_f32_16x16x32_bf16 v[62:65], v[160:163], v[176:179], v[62:65]
	s_barrier
	s_add_i32 s57, 0, 0x18000
	s_add_i32 s58, 0, 0x1c000
	v_add_u32_e32 v156, s57, v145
	v_add_u32_e32 v172, s58, v145
	ds_read_b128 v[140:143], v156
	ds_read_b128 v[148:151], v156 offset:1024
	ds_read_b128 v[152:155], v156 offset:2048
	ds_read_b128 v[156:159], v156 offset:3072
	ds_read_b128 v[160:163], v172
	ds_read_b128 v[164:167], v172 offset:1024
	ds_read_b128 v[168:171], v172 offset:2048
	ds_read_b128 v[172:175], v172 offset:3072
	s_add_u32 s38, s38, 0x40000
	s_addc_u32 s39, s39, 0
	s_mov_b32 m0, s45
	ds_read_b128 v[176:179], v147 offset:32768
	ds_read_b128 v[180:183], v147 offset:33792
	ds_read_b128 v[184:187], v147 offset:34816
	ds_read_b128 v[188:191], v147 offset:35840
	ds_read_b128 v[192:195], v147 offset:36864
	ds_read_b128 v[196:199], v147 offset:37888
	ds_read_b128 v[200:203], v147 offset:38912
	ds_read_b128 v[204:207], v147 offset:39936
	global_load_lds_dwordx4 v130, s[38:39]
	v_lshl_add_u64 v[216:217], s[38:39], 0, v[132:133]
	s_mov_b32 m0, s47
	s_nop 0
	global_load_lds_dwordx4 v[216:217], off
	s_waitcnt vmcnt(8)
	s_waitcnt lgkmcnt(0)
	s_barrier
	s_waitcnt lgkmcnt(0)
	v_mfma_f32_16x16x32_bf16 v[122:125], v[140:143], v[176:179], v[122:125]
	v_mfma_f32_16x16x32_bf16 v[122:125], v[148:151], v[180:183], v[122:125]
	v_mfma_f32_16x16x32_bf16 v[114:117], v[156:159], v[180:183], v[114:117]
	v_mfma_f32_16x16x32_bf16 v[114:117], v[152:155], v[176:179], v[114:117]
	v_mfma_f32_16x16x32_bf16 v[98:101], v[152:155], v[184:187], v[98:101]
	v_mfma_f32_16x16x32_bf16 v[98:101], v[156:159], v[188:191], v[98:101]
	v_mfma_f32_16x16x32_bf16 v[106:109], v[148:151], v[188:191], v[106:109]
	v_mfma_f32_16x16x32_bf16 v[106:109], v[140:143], v[184:187], v[106:109]
	v_mfma_f32_16x16x32_bf16 v[90:93], v[140:143], v[192:195], v[90:93]
	v_mfma_f32_16x16x32_bf16 v[90:93], v[148:151], v[196:199], v[90:93]
	v_mfma_f32_16x16x32_bf16 v[82:85], v[156:159], v[196:199], v[82:85]
	v_mfma_f32_16x16x32_bf16 v[82:85], v[152:155], v[192:195], v[82:85]
	v_mfma_f32_16x16x32_bf16 v[66:69], v[152:155], v[200:203], v[66:69]
	v_mfma_f32_16x16x32_bf16 v[66:69], v[156:159], v[204:207], v[66:69]
	v_mfma_f32_16x16x32_bf16 v[74:77], v[148:151], v[204:207], v[74:77]
	v_mfma_f32_16x16x32_bf16 v[74:77], v[140:143], v[200:203], v[74:77]
	v_mfma_f32_16x16x32_bf16 v[78:81], v[160:163], v[200:203], v[78:81]
	v_mfma_f32_16x16x32_bf16 v[78:81], v[164:167], v[204:207], v[78:81]
	v_mfma_f32_16x16x32_bf16 v[70:73], v[172:175], v[204:207], v[70:73]
	v_mfma_f32_16x16x32_bf16 v[70:73], v[168:171], v[200:203], v[70:73]
	v_mfma_f32_16x16x32_bf16 v[86:89], v[168:171], v[192:195], v[86:89]
	v_mfma_f32_16x16x32_bf16 v[86:89], v[172:175], v[196:199], v[86:89]
	v_mfma_f32_16x16x32_bf16 v[94:97], v[164:167], v[196:199], v[94:97]
	v_mfma_f32_16x16x32_bf16 v[94:97], v[160:163], v[192:195], v[94:97]
	v_mfma_f32_16x16x32_bf16 v[110:113], v[160:163], v[184:187], v[110:113]
	v_mfma_f32_16x16x32_bf16 v[110:113], v[164:167], v[188:191], v[110:113]
	v_mfma_f32_16x16x32_bf16 v[102:105], v[172:175], v[188:191], v[102:105]
	v_mfma_f32_16x16x32_bf16 v[102:105], v[168:171], v[184:187], v[102:105]
	v_mfma_f32_16x16x32_bf16 v[118:121], v[168:171], v[176:179], v[118:121]
	v_mfma_f32_16x16x32_bf16 v[118:121], v[172:175], v[180:183], v[118:121]
	v_mfma_f32_16x16x32_bf16 v[126:129], v[164:167], v[180:183], v[126:129]
	v_mfma_f32_16x16x32_bf16 v[126:129], v[160:163], v[176:179], v[126:129]
	s_barrier
	s_add_i32 s38, s57, s43
	s_mov_b32 m0, s38
	ds_read_b128 v[176:179], v147 offset:49152
	ds_read_b128 v[180:183], v147 offset:50176
	ds_read_b128 v[184:187], v147 offset:51200
	ds_read_b128 v[188:191], v147 offset:52224
	ds_read_b128 v[192:195], v147 offset:53248
	ds_read_b128 v[196:199], v147 offset:54272
	ds_read_b128 v[200:203], v147 offset:55296
	ds_read_b128 v[204:207], v147 offset:56320
	global_load_lds_dwordx4 v0, s[64:65]
	s_add_i32 m0, s38, 0x2000
	s_add_u32 s30, s30, 0x40080
	s_addc_u32 s31, s31, 0
	s_add_i32 s38, s58, s43
	global_load_lds_dwordx4 v134, s[64:65]
	s_mov_b32 m0, s38
	s_nop 0
	global_load_lds_dwordx4 v0, s[30:31]
	s_add_i32 m0, s38, 0x2000
	s_nop 0
	global_load_lds_dwordx4 v134, s[30:31]
	s_mov_b32 m0, s49
	s_nop 0
	global_load_lds_dwordx4 v130, s[66:67]
	s_mov_b32 m0, s51
	s_nop 0
	global_load_lds_dwordx4 v132, s[66:67]
	s_waitcnt vmcnt(8)
	s_waitcnt lgkmcnt(0)
	s_barrier
	s_waitcnt lgkmcnt(0)
	v_mfma_f32_16x16x32_bf16 v[58:61], v[140:143], v[176:179], v[58:61]
	v_mfma_f32_16x16x32_bf16 v[58:61], v[148:151], v[180:183], v[58:61]
	v_mfma_f32_16x16x32_bf16 v[50:53], v[156:159], v[180:183], v[50:53]
	v_mfma_f32_16x16x32_bf16 v[50:53], v[152:155], v[176:179], v[50:53]
	v_mfma_f32_16x16x32_bf16 v[34:37], v[152:155], v[184:187], v[34:37]
	v_mfma_f32_16x16x32_bf16 v[34:37], v[156:159], v[188:191], v[34:37]
	v_mfma_f32_16x16x32_bf16 v[42:45], v[148:151], v[188:191], v[42:45]
	v_mfma_f32_16x16x32_bf16 v[42:45], v[140:143], v[184:187], v[42:45]
	v_mfma_f32_16x16x32_bf16 v[26:29], v[140:143], v[192:195], v[26:29]
	v_mfma_f32_16x16x32_bf16 v[26:29], v[148:151], v[196:199], v[26:29]
	v_mfma_f32_16x16x32_bf16 v[18:21], v[156:159], v[196:199], v[18:21]
	v_mfma_f32_16x16x32_bf16 v[18:21], v[152:155], v[192:195], v[18:21]
	v_mfma_f32_16x16x32_bf16 v[6:9], v[152:155], v[200:203], v[6:9]
	v_mfma_f32_16x16x32_bf16 v[6:9], v[156:159], v[204:207], v[6:9]
	v_mfma_f32_16x16x32_bf16 v[10:13], v[148:151], v[204:207], v[10:13]
	v_mfma_f32_16x16x32_bf16 v[10:13], v[140:143], v[200:203], v[10:13]
	v_mfma_f32_16x16x32_bf16 v[14:17], v[160:163], v[200:203], v[14:17]
	v_mfma_f32_16x16x32_bf16 v[14:17], v[164:167], v[204:207], v[14:17]
	v_mfma_f32_16x16x32_bf16 v[2:5], v[172:175], v[204:207], v[2:5]
	v_mfma_f32_16x16x32_bf16 v[2:5], v[168:171], v[200:203], v[2:5]
	v_mfma_f32_16x16x32_bf16 v[22:25], v[168:171], v[192:195], v[22:25]
	v_mfma_f32_16x16x32_bf16 v[22:25], v[172:175], v[196:199], v[22:25]
	v_mfma_f32_16x16x32_bf16 v[30:33], v[164:167], v[196:199], v[30:33]
	v_mfma_f32_16x16x32_bf16 v[30:33], v[160:163], v[192:195], v[30:33]
	v_mfma_f32_16x16x32_bf16 v[46:49], v[160:163], v[184:187], v[46:49]
	v_mfma_f32_16x16x32_bf16 v[46:49], v[164:167], v[188:191], v[46:49]
	v_mfma_f32_16x16x32_bf16 v[38:41], v[172:175], v[188:191], v[38:41]
	v_mfma_f32_16x16x32_bf16 v[38:41], v[168:171], v[184:187], v[38:41]
	v_mfma_f32_16x16x32_bf16 v[54:57], v[168:171], v[176:179], v[54:57]
	v_mfma_f32_16x16x32_bf16 v[54:57], v[172:175], v[180:183], v[54:57]
	v_mfma_f32_16x16x32_bf16 v[62:65], v[164:167], v[180:183], v[62:65]
	v_mfma_f32_16x16x32_bf16 v[62:65], v[160:163], v[176:179], v[62:65]
	s_barrier
	s_add_i32 s56, s56, 2
	s_add_u32 s28, s28, 0x100
	s_addc_u32 s29, s29, 0
	s_add_u32 s54, s54, 0x100
	s_addc_u32 s55, s55, 0
	s_cmp_gt_u32 s56, 13
	s_cbranch_scc1 .Lpeel_done_374
.LBB0_374:
	s_add_u32 s30, s28, 0xfffc0080
	s_addc_u32 s31, s29, -1
	s_add_i32 s57, 0, 0x10000
	s_cmp_eq_u32 s56, 12
	s_cselect_b32 s39, s17, s31
	s_cselect_b32 s38, s25, s30
	s_cselect_b32 s31, s15, s55
	s_cselect_b32 s30, s53, s54
	s_add_i32 s60, 0, 0x14000
	v_add_u32_e32 v156, s57, v145
	v_add_u32_e32 v172, s60, v145
	ds_read_b128 v[140:143], v156
	ds_read_b128 v[148:151], v156 offset:1024
	ds_read_b128 v[152:155], v156 offset:2048
	ds_read_b128 v[156:159], v156 offset:3072
	ds_read_b128 v[160:163], v172
	ds_read_b128 v[164:167], v172 offset:1024
	ds_read_b128 v[168:171], v172 offset:2048
	ds_read_b128 v[172:175], v172 offset:3072
	s_add_i32 m0, s27, 0xc000
	ds_read_b128 v[176:179], v147
	ds_read_b128 v[180:183], v147 offset:1024
	ds_read_b128 v[184:187], v147 offset:2048
	ds_read_b128 v[188:191], v147 offset:3072
	ds_read_b128 v[192:195], v147 offset:4096
	ds_read_b128 v[196:199], v147 offset:5120
	ds_read_b128 v[200:203], v147 offset:6144
	ds_read_b128 v[204:207], v147 offset:7168
	global_load_lds_dwordx4 v136, s[28:29]
	s_add_i32 m0, s27, 0xe000
	s_nop 0
	global_load_lds_dwordx4 v138, s[28:29]
	s_waitcnt vmcnt(8)
	s_waitcnt lgkmcnt(0)
	s_barrier
	s_waitcnt lgkmcnt(0)
	v_mfma_f32_16x16x32_bf16 v[122:125], v[140:143], v[176:179], v[122:125]
	v_mfma_f32_16x16x32_bf16 v[122:125], v[148:151], v[180:183], v[122:125]
	v_mfma_f32_16x16x32_bf16 v[114:117], v[156:159], v[180:183], v[114:117]
	v_mfma_f32_16x16x32_bf16 v[114:117], v[152:155], v[176:179], v[114:117]
	v_mfma_f32_16x16x32_bf16 v[98:101], v[152:155], v[184:187], v[98:101]
	v_mfma_f32_16x16x32_bf16 v[98:101], v[156:159], v[188:191], v[98:101]
	v_mfma_f32_16x16x32_bf16 v[106:109], v[148:151], v[188:191], v[106:109]
	v_mfma_f32_16x16x32_bf16 v[106:109], v[140:143], v[184:187], v[106:109]
	v_mfma_f32_16x16x32_bf16 v[90:93], v[140:143], v[192:195], v[90:93]
	v_mfma_f32_16x16x32_bf16 v[90:93], v[148:151], v[196:199], v[90:93]
	v_mfma_f32_16x16x32_bf16 v[82:85], v[156:159], v[196:199], v[82:85]
	v_mfma_f32_16x16x32_bf16 v[82:85], v[152:155], v[192:195], v[82:85]
	v_mfma_f32_16x16x32_bf16 v[66:69], v[152:155], v[200:203], v[66:69]
	v_mfma_f32_16x16x32_bf16 v[66:69], v[156:159], v[204:207], v[66:69]
	v_mfma_f32_16x16x32_bf16 v[74:77], v[148:151], v[204:207], v[74:77]
	v_mfma_f32_16x16x32_bf16 v[74:77], v[140:143], v[200:203], v[74:77]
	v_mfma_f32_16x16x32_bf16 v[78:81], v[160:163], v[200:203], v[78:81]
	v_mfma_f32_16x16x32_bf16 v[78:81], v[164:167], v[204:207], v[78:81]
	v_mfma_f32_16x16x32_bf16 v[70:73], v[172:175], v[204:207], v[70:73]
	v_mfma_f32_16x16x32_bf16 v[70:73], v[168:171], v[200:203], v[70:73]
	v_mfma_f32_16x16x32_bf16 v[86:89], v[168:171], v[192:195], v[86:89]
	v_mfma_f32_16x16x32_bf16 v[86:89], v[172:175], v[196:199], v[86:89]
	v_mfma_f32_16x16x32_bf16 v[94:97], v[164:167], v[196:199], v[94:97]
	v_mfma_f32_16x16x32_bf16 v[94:97], v[160:163], v[192:195], v[94:97]
	v_mfma_f32_16x16x32_bf16 v[110:113], v[160:163], v[184:187], v[110:113]
	v_mfma_f32_16x16x32_bf16 v[110:113], v[164:167], v[188:191], v[110:113]
	v_mfma_f32_16x16x32_bf16 v[102:105], v[172:175], v[188:191], v[102:105]
	v_mfma_f32_16x16x32_bf16 v[102:105], v[168:171], v[184:187], v[102:105]
	v_mfma_f32_16x16x32_bf16 v[118:121], v[168:171], v[176:179], v[118:121]
	v_mfma_f32_16x16x32_bf16 v[118:121], v[172:175], v[180:183], v[118:121]
	v_mfma_f32_16x16x32_bf16 v[126:129], v[164:167], v[180:183], v[126:129]
	v_mfma_f32_16x16x32_bf16 v[126:129], v[160:163], v[176:179], v[126:129]
	s_barrier
	s_add_i32 s57, s57, s43
	s_add_u32 s64, s30, s98
	s_addc_u32 s65, s31, s99
	s_mov_b32 m0, s57
	ds_read_b128 v[176:179], v147 offset:16384
	ds_read_b128 v[180:183], v147 offset:17408
	ds_read_b128 v[184:187], v147 offset:18432
	ds_read_b128 v[188:191], v147 offset:19456
	ds_read_b128 v[192:195], v147 offset:20480
	ds_read_b128 v[196:199], v147 offset:21504
	ds_read_b128 v[200:203], v147 offset:22528
	ds_read_b128 v[204:207], v147 offset:23552
	global_load_lds_dwordx4 v0, s[30:31]
	s_add_i32 m0, s57, 0x2000
	s_add_u32 s58, s30, 0x40000
	s_addc_u32 s59, s31, 0
	s_add_i32 s57, s60, s43
	global_load_lds_dwordx4 v134, s[30:31]
	s_mov_b32 m0, s57
	global_load_lds_dwordx4 v0, s[58:59]
	s_add_i32 m0, s57, 0x2000
	s_nop 0
	global_load_lds_dwordx4 v134, s[58:59]
	s_add_u32 s66, s38, s98
	s_addc_u32 s67, s39, s99
	s_mov_b32 m0, s27
	s_nop 0
	global_load_lds_dwordx4 v130, s[38:39]
	s_mov_b32 m0, s44
	s_nop 0
	global_load_lds_dwordx4 v132, s[38:39]
	s_waitcnt vmcnt(8)
	s_waitcnt lgkmcnt(0)
	s_barrier
	s_waitcnt lgkmcnt(0)
	v_mfma_f32_16x16x32_bf16 v[58:61], v[140:143], v[176:179], v[58:61]
	v_mfma_f32_16x16x32_bf16 v[58:61], v[148:151], v[180:183], v[58:61]
	v_mfma_f32_16x16x32_bf16 v[50:53], v[156:159], v[180:183], v[50:53]
	v_mfma_f32_16x16x32_bf16 v[50:53], v[152:155], v[176:179], v[50:53]
	v_mfma_f32_16x16x32_bf16 v[34:37], v[152:155], v[184:187], v[34:37]
	v_mfma_f32_16x16x32_bf16 v[34:37], v[156:159], v[188:191], v[34:37]
	v_mfma_f32_16x16x32_bf16 v[42:45], v[148:151], v[188:191], v[42:45]
	v_mfma_f32_16x16x32_bf16 v[42:45], v[140:143], v[184:187], v[42:45]
	v_mfma_f32_16x16x32_bf16 v[26:29], v[140:143], v[192:195], v[26:29]
	v_mfma_f32_16x16x32_bf16 v[26:29], v[148:151], v[196:199], v[26:29]
	v_mfma_f32_16x16x32_bf16 v[18:21], v[156:159], v[196:199], v[18:21]
	v_mfma_f32_16x16x32_bf16 v[18:21], v[152:155], v[192:195], v[18:21]
	v_mfma_f32_16x16x32_bf16 v[6:9], v[152:155], v[200:203], v[6:9]
	v_mfma_f32_16x16x32_bf16 v[6:9], v[156:159], v[204:207], v[6:9]
	v_mfma_f32_16x16x32_bf16 v[10:13], v[148:151], v[204:207], v[10:13]
	v_mfma_f32_16x16x32_bf16 v[10:13], v[140:143], v[200:203], v[10:13]
	v_mfma_f32_16x16x32_bf16 v[14:17], v[160:163], v[200:203], v[14:17]
	v_mfma_f32_16x16x32_bf16 v[14:17], v[164:167], v[204:207], v[14:17]
	v_mfma_f32_16x16x32_bf16 v[2:5], v[172:175], v[204:207], v[2:5]
	v_mfma_f32_16x16x32_bf16 v[2:5], v[168:171], v[200:203], v[2:5]
	v_mfma_f32_16x16x32_bf16 v[22:25], v[168:171], v[192:195], v[22:25]
	v_mfma_f32_16x16x32_bf16 v[22:25], v[172:175], v[196:199], v[22:25]
	v_mfma_f32_16x16x32_bf16 v[30:33], v[164:167], v[196:199], v[30:33]
	v_mfma_f32_16x16x32_bf16 v[30:33], v[160:163], v[192:195], v[30:33]
	v_mfma_f32_16x16x32_bf16 v[46:49], v[160:163], v[184:187], v[46:49]
	v_mfma_f32_16x16x32_bf16 v[46:49], v[164:167], v[188:191], v[46:49]
	v_mfma_f32_16x16x32_bf16 v[38:41], v[172:175], v[188:191], v[38:41]
	v_mfma_f32_16x16x32_bf16 v[38:41], v[168:171], v[184:187], v[38:41]
	v_mfma_f32_16x16x32_bf16 v[54:57], v[168:171], v[176:179], v[54:57]
	v_mfma_f32_16x16x32_bf16 v[54:57], v[172:175], v[180:183], v[54:57]
	v_mfma_f32_16x16x32_bf16 v[62:65], v[164:167], v[180:183], v[62:65]
	v_mfma_f32_16x16x32_bf16 v[62:65], v[160:163], v[176:179], v[62:65]
	s_barrier
	s_add_i32 s57, 0, 0x18000
	s_add_i32 s58, 0, 0x1c000
	v_add_u32_e32 v156, s57, v145
	v_add_u32_e32 v172, s58, v145
	ds_read_b128 v[140:143], v156
	ds_read_b128 v[148:151], v156 offset:1024
	ds_read_b128 v[152:155], v156 offset:2048
	ds_read_b128 v[156:159], v156 offset:3072
	ds_read_b128 v[160:163], v172
	ds_read_b128 v[164:167], v172 offset:1024
	ds_read_b128 v[168:171], v172 offset:2048
	ds_read_b128 v[172:175], v172 offset:3072
	s_add_u32 s38, s38, 0x40000
	s_addc_u32 s39, s39, 0
	s_mov_b32 m0, s45
	ds_read_b128 v[176:179], v147 offset:32768
	ds_read_b128 v[180:183], v147 offset:33792
	ds_read_b128 v[184:187], v147 offset:34816
	ds_read_b128 v[188:191], v147 offset:35840
	ds_read_b128 v[192:195], v147 offset:36864
	ds_read_b128 v[196:199], v147 offset:37888
	ds_read_b128 v[200:203], v147 offset:38912
	ds_read_b128 v[204:207], v147 offset:39936
	global_load_lds_dwordx4 v130, s[38:39]
	s_mov_b32 m0, s47
	s_nop 0
	global_load_lds_dwordx4 v132, s[38:39]
	s_waitcnt vmcnt(8)
	s_waitcnt lgkmcnt(0)
	s_barrier
	s_waitcnt lgkmcnt(0)
	v_mfma_f32_16x16x32_bf16 v[122:125], v[140:143], v[176:179], v[122:125]
	v_mfma_f32_16x16x32_bf16 v[122:125], v[148:151], v[180:183], v[122:125]
	v_mfma_f32_16x16x32_bf16 v[114:117], v[156:159], v[180:183], v[114:117]
	v_mfma_f32_16x16x32_bf16 v[114:117], v[152:155], v[176:179], v[114:117]
	v_mfma_f32_16x16x32_bf16 v[98:101], v[152:155], v[184:187], v[98:101]
	v_mfma_f32_16x16x32_bf16 v[98:101], v[156:159], v[188:191], v[98:101]
	v_mfma_f32_16x16x32_bf16 v[106:109], v[148:151], v[188:191], v[106:109]
	v_mfma_f32_16x16x32_bf16 v[106:109], v[140:143], v[184:187], v[106:109]
	v_mfma_f32_16x16x32_bf16 v[90:93], v[140:143], v[192:195], v[90:93]
	v_mfma_f32_16x16x32_bf16 v[90:93], v[148:151], v[196:199], v[90:93]
	v_mfma_f32_16x16x32_bf16 v[82:85], v[156:159], v[196:199], v[82:85]
	v_mfma_f32_16x16x32_bf16 v[82:85], v[152:155], v[192:195], v[82:85]
	v_mfma_f32_16x16x32_bf16 v[66:69], v[152:155], v[200:203], v[66:69]
	v_mfma_f32_16x16x32_bf16 v[66:69], v[156:159], v[204:207], v[66:69]
	v_mfma_f32_16x16x32_bf16 v[74:77], v[148:151], v[204:207], v[74:77]
	v_mfma_f32_16x16x32_bf16 v[74:77], v[140:143], v[200:203], v[74:77]
	v_mfma_f32_16x16x32_bf16 v[78:81], v[160:163], v[200:203], v[78:81]
	v_mfma_f32_16x16x32_bf16 v[78:81], v[164:167], v[204:207], v[78:81]
	v_mfma_f32_16x16x32_bf16 v[70:73], v[172:175], v[204:207], v[70:73]
	v_mfma_f32_16x16x32_bf16 v[70:73], v[168:171], v[200:203], v[70:73]
	v_mfma_f32_16x16x32_bf16 v[86:89], v[168:171], v[192:195], v[86:89]
	v_mfma_f32_16x16x32_bf16 v[86:89], v[172:175], v[196:199], v[86:89]
	v_mfma_f32_16x16x32_bf16 v[94:97], v[164:167], v[196:199], v[94:97]
	v_mfma_f32_16x16x32_bf16 v[94:97], v[160:163], v[192:195], v[94:97]
	v_mfma_f32_16x16x32_bf16 v[110:113], v[160:163], v[184:187], v[110:113]
	v_mfma_f32_16x16x32_bf16 v[110:113], v[164:167], v[188:191], v[110:113]
	v_mfma_f32_16x16x32_bf16 v[102:105], v[172:175], v[188:191], v[102:105]
	v_mfma_f32_16x16x32_bf16 v[102:105], v[168:171], v[184:187], v[102:105]
	v_mfma_f32_16x16x32_bf16 v[118:121], v[168:171], v[176:179], v[118:121]
	v_mfma_f32_16x16x32_bf16 v[118:121], v[172:175], v[180:183], v[118:121]
	v_mfma_f32_16x16x32_bf16 v[126:129], v[164:167], v[180:183], v[126:129]
	v_mfma_f32_16x16x32_bf16 v[126:129], v[160:163], v[176:179], v[126:129]
	s_barrier
	s_add_i32 s38, s57, s43
	s_mov_b32 m0, s38
	ds_read_b128 v[176:179], v147 offset:49152
	ds_read_b128 v[180:183], v147 offset:50176
	ds_read_b128 v[184:187], v147 offset:51200
	ds_read_b128 v[188:191], v147 offset:52224
	ds_read_b128 v[192:195], v147 offset:53248
	ds_read_b128 v[196:199], v147 offset:54272
	ds_read_b128 v[200:203], v147 offset:55296
	ds_read_b128 v[204:207], v147 offset:56320
	global_load_lds_dwordx4 v0, s[64:65]
	s_add_i32 m0, s38, 0x2000
	s_add_u32 s30, s30, 0x40080
	s_addc_u32 s31, s31, 0
	s_add_i32 s38, s58, s43
	global_load_lds_dwordx4 v134, s[64:65]
	s_mov_b32 m0, s38
	s_nop 0
	global_load_lds_dwordx4 v0, s[30:31]
	s_add_i32 m0, s38, 0x2000
	s_nop 0
	global_load_lds_dwordx4 v134, s[30:31]
	s_mov_b32 m0, s49
	s_nop 0
	global_load_lds_dwordx4 v130, s[66:67]
	s_mov_b32 m0, s51
	s_nop 0
	global_load_lds_dwordx4 v132, s[66:67]
	s_waitcnt vmcnt(8)
	s_waitcnt lgkmcnt(0)
	s_barrier
	s_waitcnt lgkmcnt(0)
	v_mfma_f32_16x16x32_bf16 v[58:61], v[140:143], v[176:179], v[58:61]
	v_mfma_f32_16x16x32_bf16 v[58:61], v[148:151], v[180:183], v[58:61]
	v_mfma_f32_16x16x32_bf16 v[50:53], v[156:159], v[180:183], v[50:53]
	v_mfma_f32_16x16x32_bf16 v[50:53], v[152:155], v[176:179], v[50:53]
	v_mfma_f32_16x16x32_bf16 v[34:37], v[152:155], v[184:187], v[34:37]
	v_mfma_f32_16x16x32_bf16 v[34:37], v[156:159], v[188:191], v[34:37]
	v_mfma_f32_16x16x32_bf16 v[42:45], v[148:151], v[188:191], v[42:45]
	v_mfma_f32_16x16x32_bf16 v[42:45], v[140:143], v[184:187], v[42:45]
	v_mfma_f32_16x16x32_bf16 v[26:29], v[140:143], v[192:195], v[26:29]
	v_mfma_f32_16x16x32_bf16 v[26:29], v[148:151], v[196:199], v[26:29]
	v_mfma_f32_16x16x32_bf16 v[18:21], v[156:159], v[196:199], v[18:21]
	v_mfma_f32_16x16x32_bf16 v[18:21], v[152:155], v[192:195], v[18:21]
	v_mfma_f32_16x16x32_bf16 v[6:9], v[152:155], v[200:203], v[6:9]
	v_mfma_f32_16x16x32_bf16 v[6:9], v[156:159], v[204:207], v[6:9]
	v_mfma_f32_16x16x32_bf16 v[10:13], v[148:151], v[204:207], v[10:13]
	v_mfma_f32_16x16x32_bf16 v[10:13], v[140:143], v[200:203], v[10:13]
	v_mfma_f32_16x16x32_bf16 v[14:17], v[160:163], v[200:203], v[14:17]
	v_mfma_f32_16x16x32_bf16 v[14:17], v[164:167], v[204:207], v[14:17]
	v_mfma_f32_16x16x32_bf16 v[2:5], v[172:175], v[204:207], v[2:5]
	v_mfma_f32_16x16x32_bf16 v[2:5], v[168:171], v[200:203], v[2:5]
	v_mfma_f32_16x16x32_bf16 v[22:25], v[168:171], v[192:195], v[22:25]
	v_mfma_f32_16x16x32_bf16 v[22:25], v[172:175], v[196:199], v[22:25]
	v_mfma_f32_16x16x32_bf16 v[30:33], v[164:167], v[196:199], v[30:33]
	v_mfma_f32_16x16x32_bf16 v[30:33], v[160:163], v[192:195], v[30:33]
	v_mfma_f32_16x16x32_bf16 v[46:49], v[160:163], v[184:187], v[46:49]
	v_mfma_f32_16x16x32_bf16 v[46:49], v[164:167], v[188:191], v[46:49]
	v_mfma_f32_16x16x32_bf16 v[38:41], v[172:175], v[188:191], v[38:41]
	v_mfma_f32_16x16x32_bf16 v[38:41], v[168:171], v[184:187], v[38:41]
	v_mfma_f32_16x16x32_bf16 v[54:57], v[168:171], v[176:179], v[54:57]
	v_mfma_f32_16x16x32_bf16 v[54:57], v[172:175], v[180:183], v[54:57]
	v_mfma_f32_16x16x32_bf16 v[62:65], v[164:167], v[180:183], v[62:65]
	v_mfma_f32_16x16x32_bf16 v[62:65], v[160:163], v[176:179], v[62:65]
	s_barrier
	s_add_i32 s56, s56, 2
	s_add_u32 s28, s28, 0x100
	s_addc_u32 s29, s29, 0
	s_add_u32 s54, s54, 0x100
	s_addc_u32 s55, s55, 0
	s_cmp_gt_u32 s56, 13
	s_cbranch_scc0 .LBB0_374
